# scan_pre (P15): 128 global_load_ushort switched to saddr form (SGPR array base + per-row 32-bit VGPR offset computed once per item); 240 dead 64-bit address VALU ops deleted
# speedup vs baseline: 1.0010x; 1.0010x over previous
; __device__ __forceinline__ void scan_pre(const Ctx& C, const bf16* P, const float* mu, const float* k_k, const float* k_a, const float* r_k,
;                                          const bf16* SW, const bf16* SA, const bf16* SV, const bf16* GG, unsigned char* CH) {
;     ...
;     for (int item = C.gw; item < BATCH * RH * 256; item += C.NGW) {
;         const int c = item & 255, bh = item >> 8, b = bh / RH, hh = bh % RH, cj = hh * 64 + lane;
;         const float mur = mu[PB_R + cj], muk = mu[PB_K + cj], kkj = k_k[cj], kaj = k_a[cj], rkj = r_k[cj];
;         unsigned char* rec = CH + (size_t)item * CH_REC;
;         float rr[16], k2[16], aa[16], bb[16], ww[16]; unsigned vv[16], gg_[16]; float bon = 0.f;
; #pragma unroll
;         for (int t = 0; t < 16; ++t) { const int tt = 16 * c + t; const size_t row = (size_t)b * SEQ + tt;
;             const bf16* pp = P + row * LDP + cj; const bf16* pq = (tt > 0) ? (pp - LDP) : pp;
;             const unsigned pr = pp[PB_R], pk = pp[PB_K], pr1 = pq[PB_R], pk1 = pq[PB_K];
;             const size_t o = row * MIXW + cj; const float as = bf2f(SA[o]); ww[t] = bf2f(SW[o]); vv[t] = SV[o]; gg_[t] = GG[o];
;             const float rc = bflo(pr), kc = bflo(pk), rp = (tt > 0) ? bflo(pr1) : 0.f, kp = (tt > 0) ? bflo(pk1) : 0.f;
;             const float r = rc + (rp - rc) * mur, k = kc + (kp - kc) * muk;
;             float kk = k * kkj; const float nrm = sqrtf(wave_sum_dpp(kk * kk)); kk = kk / fmaxf(nrm, 1e-12f);
;             rr[t] = r; aa[t] = -kk; bb[t] = kk * as; k2[t] = k * (1.f + (as - 1.f) * kaj);
;             const float bt = wave_sum_dpp(r * k2[t] * rkj); if (lane == t) bon = bt; }
.LBB0_1272:
	s_ashr_i32 s7, s89, 8
	s_mul_hi_i32 s6, s7, 0x2aaaaaab
	s_lshr_b32 s8, s6, 31
	s_ashr_i32 s6, s6, 3
	s_add_i32 s6, s6, s8
	s_mul_i32 s8, s6, 48
	s_sub_i32 s7, s7, s8
	v_lshl_or_b32 v8, s7, 6, v1
	s_ashr_i32 s7, s6, 31
	s_waitcnt lgkmcnt(0)
	s_and_b32 s12, s93, 0xff0
	s_lshl_b64 s[8:9], s[6:7], 12
	s_or_b32 s6, s8, s12
	v_ashrrev_i32_e32 v9, 31, v8
	s_cmp_eq_u32 s12, 0
	s_cselect_b64 s[52:53], -1, 0
	s_mul_i32 s7, s9, 0x5800
	s_and_b64 s[10:11], s[52:53], exec
	s_cselect_b32 s11, 0, -1
	s_cselect_b32 s10, 0, 0xffffa800
	s_mul_i32 s8, s9, 0xc00
	s_or_b32 s9, s6, 1
	s_or_b32 s9, s6, 2
	s_mul_i32 s98, s6, 0x5800
	s_mul_i32 s99, s6, 0x1800
	v_lshl_add_u32 v186, v8, 1, s98
	v_lshl_add_u32 v218, v8, 1, s99
	v_add_u32_e32 v187, 0x5800, v186
	v_add_u32_e32 v188, 0xb000, v186
	v_add_u32_e32 v189, 0x10800, v186
	v_add_u32_e32 v190, 0x16000, v186
	v_add_u32_e32 v191, 0x1b800, v186
	v_add_u32_e32 v192, 0x21000, v186
	v_add_u32_e32 v193, 0x26800, v186
	v_add_u32_e32 v194, 0x2c000, v186
	v_add_u32_e32 v195, 0x31800, v186
	v_add_u32_e32 v196, 0x37000, v186
	v_add_u32_e32 v197, 0x3c800, v186
	v_add_u32_e32 v198, 0x42000, v186
	v_add_u32_e32 v199, 0x47800, v186
	v_add_u32_e32 v200, 0x4d000, v186
	v_add_u32_e32 v201, 0x52800, v186
	v_add_u32_e32 v202, 0x1800, v186
	v_add_u32_e32 v203, 0x7000, v186
	v_add_u32_e32 v204, 0xc800, v186
	v_add_u32_e32 v205, 0x12000, v186
	v_add_u32_e32 v206, 0x17800, v186
	v_add_u32_e32 v207, 0x1d000, v186
	v_add_u32_e32 v208, 0x22800, v186
	v_add_u32_e32 v209, 0x28000, v186
	v_add_u32_e32 v210, 0x2d800, v186
	v_add_u32_e32 v211, 0x33000, v186
	v_add_u32_e32 v212, 0x38800, v186
	v_add_u32_e32 v213, 0x3e000, v186
	v_add_u32_e32 v214, 0x43800, v186
	v_add_u32_e32 v215, 0x49000, v186
	v_add_u32_e32 v216, 0x4e800, v186
	v_add_u32_e32 v217, 0x54000, v186
	v_add_u32_e32 v219, 0x1800, v218
	v_add_u32_e32 v220, 0x3000, v218
	v_add_u32_e32 v221, 0x4800, v218
	v_add_u32_e32 v222, 0x6000, v218
	v_add_u32_e32 v223, 0x7800, v218
	v_add_u32_e32 v224, 0x9000, v218
	v_add_u32_e32 v225, 0xa800, v218
	v_add_u32_e32 v226, 0xc000, v218
	v_add_u32_e32 v227, 0xd800, v218
	v_add_u32_e32 v229, 0xf000, v218
	v_add_u32_e32 v230, 0x10800, v218
	v_add_u32_e32 v231, 0x12000, v218
	v_add_u32_e32 v232, 0x13800, v218
	v_add_u32_e32 v233, 0x15000, v218
	v_add_u32_e32 v234, 0x16800, v218
	v_add_u32_e32 v235, 0xffffa800, v186
	v_cndmask_b32_e64 v235, v235, v186, s[52:53]
	v_add_u32_e32 v236, 0x1800, v235
	global_load_ushort v18, v218, s[72:73]
	s_nop 0
	global_load_ushort v19, v235, s[70:71]
	global_load_ushort v40, v236, s[70:71]
	s_nop 0
	global_load_ushort v17, v219, s[72:73]
	v_lshlrev_b64 v[14:15], 2, v[8:9]
	v_lshl_add_u64 v[20:21], s[80:81], 0, v[14:15]
	global_load_dword v16, v[20:21], off
	global_load_ushort v41, v186, s[70:71]
	global_load_ushort v42, v220, s[72:73]
	global_load_ushort v43, v186, s[70:71]
	global_load_ushort v44, v187, s[70:71]
	global_load_ushort v45, v188, s[70:71]
	s_or_b32 s9, s6, 3
	s_nop 0
	s_nop 0
	s_nop 0
	s_nop 0
	s_nop 0
	global_load_ushort v60, v204, s[70:71]
	global_load_ushort v62, v187, s[70:71]
	s_nop 0
	global_load_ushort v7, v221, s[76:77]
	global_load_ushort v5, v221, s[78:79]
	s_nop 0
	global_load_ushort v38, v203, s[70:71]
	s_nop 0
	global_load_ushort v162, v221, s[74:75]
	s_nop 0
	global_load_ushort v32, v202, s[70:71]
	global_load_ushort v33, v203, s[70:71]
	global_load_ushort v39, v221, s[72:73]
	s_movk_i32 s10, 0x3000
	global_load_ushort v72, v218, s[76:77]
	global_load_ushort v52, v218, s[78:79]
	global_load_ushort v164, v219, s[74:75]
	global_load_ushort v166, v218, s[74:75]
	v_add_co_u32_e32 v2, vcc, s10, v20
	s_nop 1
	v_addc_co_u32_e32 v3, vcc, 0, v21, vcc
	global_load_dword v4, v[2:3], off
	v_lshl_add_u64 v[2:3], s[60:61], 0, v[14:15]
	global_load_dword v6, v[2:3], off
	v_lshl_add_u64 v[2:3], s[62:63], 0, v[14:15]
	v_lshl_add_u64 v[14:15], s[82:83], 0, v[14:15]
	global_load_dword v2, v[2:3], off
	global_load_dword v3, v[14:15], off
	s_waitcnt vmcnt(26)
	v_lshlrev_b32_e32 v110, 16, v18
	s_waitcnt vmcnt(25)
	v_lshlrev_b32_e32 v14, 16, v19
	global_load_ushort v75, v219, s[76:77]
	global_load_ushort v76, v220, s[76:77]
	global_load_ushort v73, v220, s[78:79]
	global_load_ushort v171, v220, s[74:75]
	global_load_ushort v74, v219, s[78:79]
	s_waitcnt vmcnt(28)
	v_lshlrev_b32_e32 v111, 16, v17
	v_cndmask_b32_e64 v15, v14, 0, s[52:53]
	v_lshlrev_b32_e32 v14, 16, v40
	v_cndmask_b32_e64 v14, v14, 0, s[52:53]
	s_waitcnt vmcnt(26)
	v_lshlrev_b32_e32 v12, 16, v41
	s_waitcnt vmcnt(25)
	v_lshlrev_b32_e32 v112, 16, v42
	s_waitcnt vmcnt(24)
	v_lshlrev_b32_e32 v163, 16, v43
	s_waitcnt vmcnt(23)
	v_lshlrev_b32_e32 v160, 16, v44
	v_sub_f32_e32 v12, v12, v160
	v_fmac_f32_e32 v160, v16, v12
	global_load_ushort v17, v189, s[70:71]
	v_sub_f32_e32 v15, v15, v163
	v_fmac_f32_e32 v163, v16, v15
	s_waitcnt vmcnt(23)
	v_lshlrev_b32_e32 v161, 16, v45
	s_or_b32 s9, s6, 4
	s_waitcnt vmcnt(22)
	v_lshlrev_b32_e32 v61, 16, v60
	s_waitcnt vmcnt(21)
	v_lshlrev_b32_e32 v18, 16, v62
	v_sub_f32_e32 v18, v18, v161
	v_fmac_f32_e32 v161, v16, v18
	s_waitcnt vmcnt(18)
	v_lshlrev_b32_e32 v64, 16, v38
	s_waitcnt vmcnt(16)
	v_lshlrev_b32_e32 v60, 16, v32
	s_waitcnt vmcnt(15)
	v_lshlrev_b32_e32 v15, 16, v33
	v_pk_add_f32 v[62:63], v[14:15], v[60:61] neg_lo:[0,1] neg_hi:[0,1]
	s_waitcnt vmcnt(14)
	v_lshlrev_b32_e32 v113, 16, v39
	s_waitcnt vmcnt(9)
	v_pk_fma_f32 v[60:61], v[4:5], v[62:63], v[60:61] op_sel_hi:[0,1,1]
	s_waitcnt vmcnt(8)
; __device__ __forceinline__ void scan_pre(const Ctx& C, const bf16* P, const float* mu, const float* k_k, const float* k_a, const float* r_k,
;                                          const bf16* SW, const bf16* SA, const bf16* SV, const bf16* GG, unsigned char* CH) {
;     ...
;         for (int t = 0; t < 16; ++t) { const int tt = 16 * c + t; const size_t row = (size_t)b * SEQ + tt;
;             const bf16* pp = P + row * LDP + cj; const bf16* pq = (tt > 0) ? (pp - LDP) : pp;
;             const unsigned pr = pp[PB_R], pk = pp[PB_K], pr1 = pq[PB_R], pk1 = pq[PB_K];
;             const size_t o = row * MIXW + cj; const float as = bf2f(SA[o]); ww[t] = bf2f(SW[o]); vv[t] = SV[o]; gg_[t] = GG[o];
;             const float rc = bflo(pr), kc = bflo(pk), rp = (tt > 0) ? bflo(pr1) : 0.f, kp = (tt > 0) ? bflo(pk1) : 0.f;
	v_pk_mul_f32 v[62:63], v[6:7], v[60:61] op_sel_hi:[0,1]
	s_nop 0
	s_or_b32 s9, s6, 5
	global_load_ushort v40, v205, s[70:71]
	global_load_ushort v41, v188, s[70:71]
	global_load_ushort v42, v202, s[70:71]
	global_load_ushort v43, v204, s[70:71]
	global_load_ushort v44, v222, s[72:73]
	s_or_b32 s9, s6, 6
	global_load_ushort v45, v189, s[70:71]
	global_load_ushort v68, v223, s[72:73]
	global_load_ushort v69, v190, s[70:71]
	global_load_ushort v70, v224, s[72:73]
	s_nop 0
	s_or_b32 s9, s6, 7
	s_nop 0
	s_waitcnt vmcnt(9)
	v_lshlrev_b32_e32 v165, 16, v17
	s_waitcnt vmcnt(8)
	v_lshlrev_b32_e32 v65, 16, v40
	s_waitcnt vmcnt(4)
	v_lshlrev_b32_e32 v152, 16, v44
	global_load_ushort v71, v206, s[70:71]
	global_load_ushort v85, v208, s[70:71]
	global_load_ushort v86, v191, s[70:71]
	global_load_ushort v87, v205, s[70:71]
	global_load_ushort v88, v207, s[70:71]
	s_nop 0
	global_load_ushort v80, v190, s[70:71]
	global_load_ushort v82, v191, s[70:71]
	global_load_ushort v84, v192, s[70:71]
	global_load_ushort v89, v193, s[70:71]
	s_nop 0
	s_nop 0
	s_or_b32 s9, s6, 8
	global_load_ushort v90, v225, s[72:73]
	global_load_ushort v78, v225, s[76:77]
	global_load_ushort v77, v225, s[78:79]
	global_load_ushort v91, v207, s[70:71]
	s_nop 0
	global_load_ushort v34, v209, s[70:71]
	s_nop 0
	global_load_ushort v35, v192, s[70:71]
	global_load_ushort v92, v206, s[70:71]
	global_load_ushort v93, v208, s[70:71]
	global_load_ushort v94, v194, s[70:71]
	s_nop 0
	global_load_ushort v95, v226, s[72:73]
	global_load_ushort v96, v193, s[70:71]
	s_or_b32 s9, s6, 9
	global_load_ushort v97, v227, s[72:73]
	global_load_ushort v17, v195, s[70:71]
	global_load_ushort v81, v222, s[76:77]
	global_load_ushort v79, v222, s[78:79]
	global_load_ushort v158, v222, s[74:75]
	v_lshlrev_b32_e32 v24, 16, v41
	v_sub_f32_e32 v24, v24, v165
	v_fmac_f32_e32 v165, v16, v24
	v_lshlrev_b32_e32 v25, 16, v43
	v_lshlrev_b32_e32 v24, 16, v42
	v_pk_add_f32 v[66:67], v[24:25], v[64:65] neg_lo:[0,1] neg_hi:[0,1]
	s_or_b32 s9, s6, 10
	s_waitcnt vmcnt(27)
	v_lshlrev_b32_e32 v153, 16, v68
	s_waitcnt vmcnt(25)
	v_lshlrev_b32_e32 v154, 16, v70
	v_pk_fma_f32 v[64:65], v[4:5], v[66:67], v[64:65] op_sel_hi:[0,1,1]
	v_pk_mul_f32 v[66:67], v[6:7], v[64:65] op_sel_hi:[0,1]
	s_waitcnt vmcnt(19)
	v_lshlrev_b32_e32 v151, 16, v80
	global_load_ushort v83, v223, s[76:77]
	global_load_ushort v159, v224, s[74:75]
	global_load_ushort v80, v223, s[78:79]
	global_load_ushort v156, v223, s[74:75]
	v_lshlrev_b32_e32 v18, 16, v45
	v_sub_f32_e32 v18, v18, v151
	v_fmac_f32_e32 v151, v16, v18
	s_waitcnt vmcnt(22)
	v_lshlrev_b32_e32 v150, 16, v82
	v_lshlrev_b32_e32 v18, 16, v69
	v_sub_f32_e32 v18, v18, v150
	v_fmac_f32_e32 v150, v16, v18
	s_waitcnt vmcnt(21)
	v_lshlrev_b32_e32 v148, 16, v84
	global_load_ushort v84, v224, s[76:77]
	global_load_ushort v157, v225, s[74:75]
	global_load_ushort v82, v224, s[78:79]
	v_lshlrev_b32_e32 v18, 16, v86
	v_sub_f32_e32 v18, v18, v148
	v_lshlrev_b32_e32 v27, 16, v85
	v_lshlrev_b32_e32 v26, 16, v71
	v_fmac_f32_e32 v148, v16, v18
	v_lshlrev_b32_e32 v19, 16, v88
	v_lshlrev_b32_e32 v18, 16, v87
	v_pk_add_f32 v[44:45], v[18:19], v[26:27] neg_lo:[0,1] neg_hi:[0,1]
	s_waitcnt vmcnt(23)
	v_lshlrev_b32_e32 v149, 16, v89
	s_waitcnt vmcnt(19)
	v_lshlrev_b32_e32 v36, 16, v91
	s_waitcnt vmcnt(18)
	v_lshlrev_b32_e32 v37, 16, v34
	s_waitcnt vmcnt(17)
	v_lshlrev_b32_e32 v18, 16, v35
	v_sub_f32_e32 v18, v18, v149
	v_fmac_f32_e32 v149, v16, v18
	s_waitcnt vmcnt(15)
	v_lshlrev_b32_e32 v19, 16, v93
	v_lshlrev_b32_e32 v18, 16, v92
	v_pk_add_f32 v[38:39], v[18:19], v[36:37] neg_lo:[0,1] neg_hi:[0,1]
	global_load_ushort v86, v226, s[76:77]
	global_load_ushort v87, v227, s[76:77]
	global_load_ushort v142, v227, s[74:75]
	global_load_ushort v85, v226, s[78:79]
	global_load_ushort v145, v226, s[74:75]
	s_waitcnt vmcnt(19)
	v_lshlrev_b32_e32 v109, 16, v94
	s_waitcnt vmcnt(17)
	v_lshlrev_b32_e32 v14, 16, v96
	v_sub_f32_e32 v14, v14, v109
	v_fmac_f32_e32 v109, v16, v14
	s_nop 0
	v_lshlrev_b32_e32 v172, 16, v95
	global_load_ushort v91, v196, s[70:71]
	s_waitcnt vmcnt(16)
	v_lshlrev_b32_e32 v108, 16, v17
	global_load_ushort v17, v194, s[70:71]
	global_load_ushort v93, v229, s[72:73]
	global_load_ushort v94, v210, s[70:71]
	global_load_ushort v95, v212, s[70:71]
	s_or_b32 s9, s6, 11
	s_nop 0
	s_nop 0
	s_nop 0
	v_lshlrev_b32_e32 v173, 16, v97
	global_load_ushort v96, v195, s[70:71]
	global_load_ushort v97, v209, s[70:71]
	global_load_ushort v98, v211, s[70:71]
	global_load_ushort v99, v230, s[72:73]
	global_load_ushort v100, v211, s[70:71]
	s_or_b32 s9, s6, 12
	s_nop 0
	global_load_ushort v101, v197, s[70:71]
	s_nop 0
	s_nop 0
	s_nop 0
	s_or_b32 s9, s6, 13
	global_load_ushort v102, v213, s[70:71]
	global_load_ushort v103, v196, s[70:71]
	global_load_ushort v104, v210, s[70:71]
	global_load_ushort v105, v212, s[70:71]
	global_load_ushort v107, v231, s[72:73]
	s_or_b32 s9, s6, 14
	global_load_ushort v167, v197, s[70:71]
	global_load_ushort v168, v232, s[72:73]
	global_load_ushort v169, v198, s[70:71]
	global_load_ushort v170, v233, s[72:73]
	s_nop 0
	s_or_b32 s6, s6, 15
	s_nop 0
	s_nop 0
	s_nop 0
	s_nop 0
	global_load_ushort v174, v214, s[70:71]
	global_load_ushort v175, v216, s[70:71]
	global_load_ushort v176, v199, s[70:71]
	global_load_ushort v177, v213, s[70:71]
	s_nop 0
	global_load_ushort v70, v215, s[70:71]
	global_load_ushort v71, v198, s[70:71]
	global_load_ushort v178, v199, s[70:71]
	global_load_ushort v179, v200, s[70:71]
	global_load_ushort v180, v201, s[70:71]
	s_nop 0
	s_nop 0
	s_nop 0
	v_lshlrev_b32_e32 v155, 16, v90
	global_load_ushort v8, v234, s[72:73]
	s_nop 0
	global_load_ushort v90, v234, s[76:77]
	global_load_ushort v9, v234, s[78:79]
	s_nop 0
	global_load_ushort v40, v217, s[70:71]
	s_nop 0
	global_load_ushort v41, v200, s[70:71]
	s_nop 0
	global_load_ushort v68, v214, s[70:71]
	global_load_ushort v69, v216, s[70:71]
	global_load_ushort v181, v215, s[70:71]
	global_load_ushort v92, v229, s[76:77]
	global_load_ushort v88, v229, s[78:79]
	global_load_ushort v147, v229, s[74:75]
	global_load_ushort v89, v227, s[78:79]
	s_waitcnt vmcnt(39)
; __device__ __forceinline__ unsigned f2bf(float f) { unsigned u = __builtin_bit_cast(unsigned, f); return (u + 0x7fffu + ((u >> 16) & 1u)) >> 16; }
; __device__ __forceinline__ void scan_pre(const Ctx& C, const bf16* P, const float* mu, const float* k_k, const float* k_a, const float* r_k,
;                                          const bf16* SW, const bf16* SA, const bf16* SV, const bf16* GG, unsigned char* CH) {
;     ...
;         for (int t = 0; t < 16; ++t) { const int tt = 16 * c + t; const size_t row = (size_t)b * SEQ + tt;
;             const bf16* pp = P + row * LDP + cj; const bf16* pq = (tt > 0) ? (pp - LDP) : pp;
;             const unsigned pr = pp[PB_R], pk = pp[PB_K], pr1 = pq[PB_R], pk1 = pq[PB_K];
;             const size_t o = row * MIXW + cj; const float as = bf2f(SA[o]); ww[t] = bf2f(SW[o]); vv[t] = SV[o]; gg_[t] = GG[o];
;             const float rc = bflo(pr), kc = bflo(pk), rp = (tt > 0) ? bflo(pr1) : 0.f, kp = (tt > 0) ? bflo(pk1) : 0.f;
;             const float r = rc + (rp - rc) * mur, k = kc + (kp - kc) * muk;
;             float kk = k * kkj; const float nrm = sqrtf(wave_sum_dpp(kk * kk)); kk = kk / fmaxf(nrm, 1e-12f);
;             rr[t] = r; aa[t] = -kk; bb[t] = kk * as; k2[t] = k * (1.f + (as - 1.f) * kaj);
;             const float bt = wave_sum_dpp(r * k2[t] * rkj); if (lane == t) bon = bt; }
;         float p = 1.f, cs_ = 0.f, ip[16];
; #pragma unroll
;         for (int t = 0; t < 16; ++t) { const float pm1 = p; cs_ += ww[t]; p = __expf(cs_); ip[t] = __expf(-cs_);
;             LAt[t * 64 + lane] = (unsigned short)f2bf(aa[t] * pm1); LRt[t * 64 + lane] = (unsigned short)f2bf(rr[t] * p);
;             LBt[t * 64 + lane] = (unsigned short)f2bf(bb[t] * ip[t]); LKt[t * 64 + lane] = (unsigned short)f2bf(k2[t] * ip[t]); }
	v_lshlrev_b32_e32 v10, 16, v17
	v_sub_f32_e32 v10, v10, v108
	v_fmac_f32_e32 v108, v16, v10
	v_lshlrev_b32_e32 v143, 16, v91
	s_waitcnt vmcnt(37)
	v_lshlrev_b32_e32 v32, 16, v94
	global_load_ushort v94, v230, s[76:77]
	global_load_ushort v91, v230, s[78:79]
	global_load_ushort v146, v230, s[74:75]
	s_waitcnt vmcnt(38)
	v_lshlrev_b32_e32 v10, 16, v96
	v_sub_f32_e32 v10, v10, v143
	v_lshlrev_b32_e32 v33, 16, v95
	v_fmac_f32_e32 v143, v16, v10
	s_waitcnt vmcnt(36)
	v_lshlrev_b32_e32 v11, 16, v98
	v_lshlrev_b32_e32 v10, 16, v97
	v_pk_add_f32 v[34:35], v[10:11], v[32:33] neg_lo:[0,1] neg_hi:[0,1]
	v_lshlrev_b32_e32 v23, 16, v93
	s_waitcnt vmcnt(33)
	v_lshlrev_b32_e32 v144, 16, v101
	global_load_ushort v96, v231, s[76:77]
	global_load_ushort v93, v231, s[78:79]
	global_load_ushort v106, v231, s[74:75]
	s_waitcnt vmcnt(34)
	v_lshlrev_b32_e32 v10, 16, v103
	v_sub_f32_e32 v10, v10, v144
	v_lshlrev_b32_e32 v29, 16, v102
	v_lshlrev_b32_e32 v28, 16, v100
	v_fmac_f32_e32 v144, v16, v10
	s_waitcnt vmcnt(32)
	v_lshlrev_b32_e32 v11, 16, v105
	v_lshlrev_b32_e32 v10, 16, v104
	v_pk_add_f32 v[30:31], v[10:11], v[28:29] neg_lo:[0,1] neg_hi:[0,1]
	s_waitcnt vmcnt(31)
	v_lshlrev_b32_e32 v183, 16, v107
	global_load_ushort v98, v232, s[76:77]
	global_load_ushort v107, v233, s[74:75]
	global_load_ushort v95, v232, s[78:79]
	global_load_ushort v104, v232, s[74:75]
	s_waitcnt vmcnt(34)
	v_lshlrev_b32_e32 v10, 16, v167
	v_lshlrev_b32_e32 v182, 16, v99
	s_waitcnt vmcnt(33)
	v_lshlrev_b32_e32 v184, 16, v168
	v_pk_fma_f32 v[44:45], v[4:5], v[44:45], v[26:27] op_sel_hi:[0,1,1]
	v_mov_b32_e32 v27, 0
	s_waitcnt vmcnt(30)
	v_lshlrev_b32_e32 v18, 16, v174
	s_waitcnt vmcnt(29)
	v_lshlrev_b32_e32 v19, 16, v175
	v_mov_b32_e32 v175, 0
	v_pk_fma_f32 v[36:37], v[4:5], v[38:39], v[36:37] op_sel_hi:[0,1,1]
	s_waitcnt vmcnt(25)
	v_lshlrev_b32_e32 v103, 16, v71
	v_sub_f32_e32 v10, v10, v103
	v_fmac_f32_e32 v103, v16, v10
	s_waitcnt vmcnt(24)
	v_lshlrev_b32_e32 v102, 16, v178
	v_lshlrev_b32_e32 v10, 16, v169
	v_sub_f32_e32 v10, v10, v102
	v_fmac_f32_e32 v102, v16, v10
	s_waitcnt vmcnt(23)
	v_lshlrev_b32_e32 v100, 16, v179
	global_load_ushort v99, v233, s[76:77]
	global_load_ushort v105, v234, s[74:75]
	global_load_ushort v97, v233, s[78:79]
	v_lshlrev_b32_e32 v10, 16, v176
	v_sub_f32_e32 v10, v10, v100
	v_add_f32_e32 v12, 0, v110
	v_fmac_f32_e32 v100, v16, v10
	v_lshlrev_b32_e32 v11, 16, v70
	v_lshlrev_b32_e32 v10, 16, v177
	v_mul_f32_e32 v13, 0x3fb8aa3b, v12
	v_pk_add_f32 v[20:21], v[10:11], v[18:19] neg_lo:[0,1] neg_hi:[0,1]
	s_waitcnt vmcnt(25)
	v_lshlrev_b32_e32 v101, 16, v180
	v_exp_f32_e32 v180, v13
	v_lshlrev_b32_e32 v178, 16, v170
	s_waitcnt vmcnt(24)
	v_lshlrev_b32_e32 v8, 16, v8
	v_mov_b32_e32 v177, 0
	v_pk_mul_f32 v[38:39], v[6:7], v[36:37] op_sel_hi:[0,1]
	s_waitcnt vmcnt(21)
	v_lshlrev_b32_e32 v15, 16, v40
	s_waitcnt vmcnt(20)
	v_lshlrev_b32_e32 v10, 16, v41
	v_sub_f32_e32 v10, v10, v101
	v_fmac_f32_e32 v101, v16, v10
	s_waitcnt vmcnt(17)
	v_lshlrev_b32_e32 v14, 16, v181
	v_lshlrev_b32_e32 v11, 16, v69
	v_lshlrev_b32_e32 v10, 16, v68
	v_pk_add_f32 v[16:17], v[10:11], v[14:15] neg_lo:[0,1] neg_hi:[0,1]
	v_mul_f32_e32 v10, 0xbfb8aa3b, v12
	v_exp_f32_e32 v68, v10
	v_mul_f32_e32 v10, v163, v180
	v_bfe_u32 v11, v10, 16, 1
	v_add3_u32 v10, v10, v11, s66
	v_add_f32_e32 v11, v12, v111
	v_mul_f32_e32 v12, 0x3fb8aa3b, v11
	v_exp_f32_e32 v181, v12
	ds_write_b16_d16_hi v114, v10 offset:2048
	v_mul_f32_e32 v10, 0xbfb8aa3b, v11
	v_exp_f32_e32 v70, v10
	v_mul_f32_e32 v10, v160, v181
	v_bfe_u32 v12, v10, 16, 1
	v_add_f32_e32 v11, v11, v112
	v_add3_u32 v10, v10, v12, s66
	v_mul_f32_e32 v12, 0x3fb8aa3b, v11
	v_exp_f32_e32 v185, v12
	ds_write_b16_d16_hi v114, v10 offset:2176
	v_mul_f32_e32 v10, 0xbfb8aa3b, v11
	v_exp_f32_e32 v69, v10
	v_mul_f32_e32 v10, v161, v185
	v_bfe_u32 v12, v10, 16, 1
	v_add_f32_e32 v11, v11, v113
	v_add3_u32 v10, v10, v12, s66
	v_mul_f32_e32 v12, 0x3fb8aa3b, v11
	v_exp_f32_e32 v167, v12
	ds_write_b16_d16_hi v114, v10 offset:2304
	v_mul_f32_e32 v10, 0xbfb8aa3b, v11
	v_exp_f32_e32 v71, v10
	v_mul_f32_e32 v10, v165, v167
	v_bfe_u32 v12, v10, 16, 1
	v_add_f32_e32 v11, v11, v152
	v_add3_u32 v10, v10, v12, s66
	v_mul_f32_e32 v12, 0x3fb8aa3b, v11
	v_exp_f32_e32 v168, v12
	ds_write_b16_d16_hi v114, v10 offset:2432
	v_mul_f32_e32 v10, 0xbfb8aa3b, v11
	v_exp_f32_e32 v40, v10
	v_mul_f32_e32 v10, v151, v168
	v_bfe_u32 v12, v10, 16, 1
	v_add_f32_e32 v11, v11, v153
	v_add3_u32 v10, v10, v12, s66
	v_mul_f32_e32 v12, 0x3fb8aa3b, v11
	v_exp_f32_e32 v169, v12
	ds_write_b16_d16_hi v114, v10 offset:2560
	v_mul_f32_e32 v10, 0xbfb8aa3b, v11
	v_exp_f32_e32 v42, v10
	v_mul_f32_e32 v10, v150, v169
	v_bfe_u32 v12, v10, 16, 1
	v_add_f32_e32 v11, v11, v154
	v_add3_u32 v10, v10, v12, s66
	v_mul_f32_e32 v12, 0x3fb8aa3b, v11
	v_exp_f32_e32 v170, v12
	ds_write_b16_d16_hi v114, v10 offset:2688
	v_mul_f32_e32 v10, 0xbfb8aa3b, v11
	v_exp_f32_e32 v41, v10
	v_mul_f32_e32 v10, v148, v170
	v_bfe_u32 v12, v10, 16, 1
	v_add_f32_e32 v11, v11, v155
	v_add3_u32 v10, v10, v12, s66
	v_mul_f32_e32 v12, 0x3fb8aa3b, v11
	v_exp_f32_e32 v152, v12
	ds_write_b16_d16_hi v114, v10 offset:2816
	v_mul_f32_e32 v10, 0xbfb8aa3b, v11
	v_exp_f32_e32 v43, v10
	v_mul_f32_e32 v10, v149, v152
	v_bfe_u32 v12, v10, 16, 1
	v_add_f32_e32 v11, v11, v172
	v_add3_u32 v10, v10, v12, s66
	v_mul_f32_e32 v12, 0x3fb8aa3b, v11
	v_exp_f32_e32 v153, v12
	ds_write_b16_d16_hi v114, v10 offset:2944
	v_mul_f32_e32 v10, 0xbfb8aa3b, v11
	v_exp_f32_e32 v22, v10
	v_mul_f32_e32 v10, v109, v153
	v_bfe_u32 v12, v10, 16, 1
	v_add_f32_e32 v11, v11, v173
	v_add3_u32 v10, v10, v12, s66
	v_mul_f32_e32 v12, 0x3fb8aa3b, v11
	v_exp_f32_e32 v154, v12
; __device__ __forceinline__ unsigned f2bf(float f) { unsigned u = __builtin_bit_cast(unsigned, f); return (u + 0x7fffu + ((u >> 16) & 1u)) >> 16; }
; __device__ __forceinline__ void scan_pre(const Ctx& C, const bf16* P, const float* mu, const float* k_k, const float* k_a, const float* r_k,
;                                          const bf16* SW, const bf16* SA, const bf16* SV, const bf16* GG, unsigned char* CH) {
;     ...
;             float kk = k * kkj; const float nrm = sqrtf(wave_sum_dpp(kk * kk)); kk = kk / fmaxf(nrm, 1e-12f);
;             rr[t] = r; aa[t] = -kk; bb[t] = kk * as; k2[t] = k * (1.f + (as - 1.f) * kaj);
;             const float bt = wave_sum_dpp(r * k2[t] * rkj); if (lane == t) bon = bt; }
;         float p = 1.f, cs_ = 0.f, ip[16];
; #pragma unroll
;         for (int t = 0; t < 16; ++t) { const float pm1 = p; cs_ += ww[t]; p = __expf(cs_); ip[t] = __expf(-cs_);
;             LAt[t * 64 + lane] = (unsigned short)f2bf(aa[t] * pm1); LRt[t * 64 + lane] = (unsigned short)f2bf(rr[t] * p);
;             LBt[t * 64 + lane] = (unsigned short)f2bf(bb[t] * ip[t]); LKt[t * 64 + lane] = (unsigned short)f2bf(k2[t] * ip[t]); }
	ds_write_b16_d16_hi v114, v10 offset:3072
	v_mul_f32_e32 v10, 0xbfb8aa3b, v11
	v_exp_f32_e32 v24, v10
	v_mul_f32_e32 v10, v108, v154
	v_bfe_u32 v12, v10, 16, 1
	v_add_f32_e32 v11, v11, v23
	v_add3_u32 v10, v10, v12, s66
	v_mul_f32_e32 v12, 0x3fb8aa3b, v11
	v_exp_f32_e32 v155, v12
	ds_write_b16_d16_hi v114, v10 offset:3200
	v_mul_f32_e32 v10, 0xbfb8aa3b, v11
	v_exp_f32_e32 v23, v10
	v_mul_f32_e32 v10, v143, v155
	v_bfe_u32 v12, v10, 16, 1
	v_add_f32_e32 v11, v11, v182
	v_add3_u32 v10, v10, v12, s66
	v_mul_f32_e32 v12, 0x3fb8aa3b, v11
	v_exp_f32_e32 v110, v12
	ds_write_b16_d16_hi v114, v10 offset:3328
	v_mul_f32_e32 v10, 0xbfb8aa3b, v11
	v_exp_f32_e32 v25, v10
	v_mul_f32_e32 v10, v144, v110
	v_bfe_u32 v12, v10, 16, 1
	v_add_f32_e32 v11, v11, v183
	v_add3_u32 v10, v10, v12, s66
	v_mul_f32_e32 v12, 0x3fb8aa3b, v11
	v_exp_f32_e32 v111, v12
	ds_write_b16_d16_hi v114, v10 offset:3456
	v_mul_f32_e32 v10, 0xbfb8aa3b, v11
	v_add_f32_e32 v11, v11, v184
	v_mul_f32_e32 v12, v103, v111
	v_bfe_u32 v13, v12, 16, 1
	v_add3_u32 v12, v12, v13, s66
	v_mul_f32_e32 v13, 0x3fb8aa3b, v11
	v_exp_f32_e32 v112, v13
	v_add_f32_e32 v172, v11, v178
	ds_write_b16_d16_hi v114, v12 offset:3584
	v_mul_f32_e32 v12, 0xbfb8aa3b, v11
	v_mul_f32_e32 v13, v102, v112
	v_bfe_u32 v113, v13, 16, 1
	v_mul_f32_e32 v11, 0x3fb8aa3b, v172
	v_add3_u32 v13, v13, v113, s66
	v_exp_f32_e32 v113, v11
	ds_write_b16_d16_hi v114, v13 offset:3712
	v_mul_f32_e32 v11, 0xbfb8aa3b, v172
	v_add_f32_e32 v172, v172, v8
	v_mul_f32_e32 v13, v100, v113
	v_bfe_u32 v173, v13, 16, 1
	v_add3_u32 v13, v13, v173, s66
	v_mul_f32_e32 v8, 0x3fb8aa3b, v172
	ds_write_b16_d16_hi v114, v13 offset:3840
	v_mul_f32_e32 v13, 0xbfb8aa3b, v172
	v_pk_mul_f32 v[172:173], v[62:63], v[62:63]
	v_exp_f32_e32 v8, v8
	v_pk_fma_f32 v[32:33], v[4:5], v[34:35], v[32:33] op_sel_hi:[0,1,1]
	v_add_f32_dpp v172, v172, v172 quad_perm:[1,0,3,2] row_mask:0xf bank_mask:0xf bound_ctrl:1
	v_add_f32_dpp v173, v173, v173 quad_perm:[1,0,3,2] row_mask:0xf bank_mask:0xf bound_ctrl:1
	v_mul_f32_e32 v174, v101, v8
	v_add_f32_dpp v172, v172, v172 quad_perm:[2,3,0,1] row_mask:0xf bank_mask:0xf bound_ctrl:1
	v_add_f32_dpp v173, v173, v173 quad_perm:[2,3,0,1] row_mask:0xf bank_mask:0xf bound_ctrl:1
	v_bfe_u32 v176, v174, 16, 1
	v_add_f32_dpp v172, v172, v172 row_half_mirror row_mask:0xf bank_mask:0xf bound_ctrl:1
	v_add_f32_dpp v173, v173, v173 row_half_mirror row_mask:0xf bank_mask:0xf bound_ctrl:1
	v_add3_u32 v174, v174, v176, s66
	v_add_f32_dpp v172, v172, v172 row_mirror row_mask:0xf bank_mask:0xf bound_ctrl:1
	v_add_f32_dpp v173, v173, v173 row_mirror row_mask:0xf bank_mask:0xf bound_ctrl:1
	ds_write_b16_d16_hi v114, v174 offset:3968
	v_mov_b32_dpp v175, v172 row_bcast:15 row_mask:0xa bank_mask:0xf
	v_add_f32_e32 v172, v172, v175
	v_mov_b32_e32 v175, 0
	v_mov_b32_dpp v177, v173 row_bcast:15 row_mask:0xa bank_mask:0xf
	v_add_f32_e32 v173, v173, v177
	v_mov_b32_dpp v175, v172 row_bcast:31 row_mask:0xc bank_mask:0xf
	v_add_f32_e32 v172, v172, v175
	v_mov_b32_e32 v177, 0
	v_readlane_b32 s6, v172, 63
	v_pk_mul_f32 v[34:35], v[6:7], v[32:33] op_sel_hi:[0,1]
	v_mov_b32_dpp v177, v173 row_bcast:31 row_mask:0xc bank_mask:0xf
	v_mul_f32_e32 v172, s6, v140
	v_mov_b32_e32 v175, s6
	v_cmp_lt_f32_e32 vcc, s6, v139
	v_add_f32_e32 v173, v173, v177
	v_pk_fma_f32 v[28:29], v[4:5], v[30:31], v[28:29] op_sel_hi:[0,1,1]
	v_cndmask_b32_e32 v172, v175, v172, vcc
	v_sqrt_f32_e32 v175, v172
	v_readlane_b32 s6, v173, 63
	v_pk_mul_f32 v[30:31], v[6:7], v[28:29] op_sel_hi:[0,1]
	v_pk_fma_f32 v[18:19], v[4:5], v[20:21], v[18:19] op_sel_hi:[0,1,1]
	v_add_u32_e32 v174, -1, v175
	v_fma_f32 v176, -v174, v175, v172
	v_cmp_ge_f32_e64 s[52:53], 0, v176
	v_mul_f32_e32 v173, s6, v140
	v_mov_b32_e32 v177, s6
	v_cndmask_b32_e64 v174, v175, v174, s[52:53]
	v_cmp_lt_f32_e64 s[52:53], s6, v139
	v_add_u32_e32 v176, 1, v175
	v_fma_f32 v175, -v176, v175, v172
	v_cndmask_b32_e64 v173, v177, v173, s[52:53]
	v_sqrt_f32_e32 v177, v173
	v_cmp_lt_f32_e64 s[54:55], 0, v175
	v_pk_mul_f32 v[20:21], v[6:7], v[18:19] op_sel_hi:[0,1]
	v_pk_fma_f32 v[14:15], v[4:5], v[16:17], v[14:15] op_sel_hi:[0,1,1]
	v_cndmask_b32_e64 v174, v174, v176, s[54:55]
	v_mul_f32_e32 v175, 0x37800000, v174
	v_cndmask_b32_e32 v174, v174, v175, vcc
	v_add_u32_e32 v175, -1, v177
	v_fma_f32 v176, -v175, v177, v173
	v_cmp_ge_f32_e32 vcc, 0, v176
	v_add_u32_e32 v176, 1, v177
	v_pk_mul_f32 v[16:17], v[6:7], v[14:15] op_sel_hi:[0,1]
	v_cndmask_b32_e32 v175, v177, v175, vcc
	v_fma_f32 v177, -v176, v177, v173
	v_cmp_lt_f32_e32 vcc, 0, v177
	v_exp_f32_e32 v10, v10
	v_exp_f32_e32 v11, v11
	v_cndmask_b32_e32 v175, v175, v176, vcc
	v_mul_f32_e32 v176, 0x37800000, v175
	v_cndmask_b32_e64 v175, v175, v176, s[52:53]
	v_cmp_class_f32_e32 vcc, v173, v134
	v_exp_f32_e32 v12, v12
	v_exp_f32_e32 v13, v13
	v_cndmask_b32_e32 v173, v175, v173, vcc
	v_max_f32_e32 v173, 0x2b8cbccc, v173
	v_div_scale_f32 v175, s[6:7], v173, v173, v63
	v_rcp_f32_e32 v176, v175
	v_cmp_class_f32_e32 vcc, v172, v134
	v_lshl_or_b32 v5, v5, 16, v73
	s_nop 0
	v_cndmask_b32_e32 v172, v174, v172, vcc
	v_fma_f32 v174, -v175, v176, 1.0
	v_fmac_f32_e32 v176, v174, v176
	v_div_scale_f32 v174, vcc, v63, v173, v63
	v_mul_f32_e32 v177, v174, v176
	v_fma_f32 v178, -v175, v177, v174
	v_max_f32_e32 v172, 0x2b8cbccc, v172
	v_fmac_f32_e32 v177, v178, v176
	v_fma_f32 v174, -v175, v177, v174
	v_div_scale_f32 v175, s[6:7], v172, v172, v62
	v_rcp_f32_e32 v178, v175
	v_div_fmas_f32 v174, v174, v176, v177
	v_div_fixup_f32 v63, v174, v173, v63
	v_mov_b32_e32 v177, 0
	v_fma_f32 v173, -v175, v178, 1.0
	v_fmac_f32_e32 v178, v173, v178
	v_div_scale_f32 v173, vcc, v62, v172, v62
	v_mul_f32_e32 v174, v173, v178
; __device__ __forceinline__ unsigned f2bf(float f) { unsigned u = __builtin_bit_cast(unsigned, f); return (u + 0x7fffu + ((u >> 16) & 1u)) >> 16; }
; __device__ __forceinline__ void scan_pre(const Ctx& C, const bf16* P, const float* mu, const float* k_k, const float* k_a, const float* r_k,
;                                          const bf16* SW, const bf16* SA, const bf16* SV, const bf16* GG, unsigned char* CH) {
;     ...
;             float kk = k * kkj; const float nrm = sqrtf(wave_sum_dpp(kk * kk)); kk = kk / fmaxf(nrm, 1e-12f);
;             rr[t] = r; aa[t] = -kk; bb[t] = kk * as; k2[t] = k * (1.f + (as - 1.f) * kaj);
;             const float bt = wave_sum_dpp(r * k2[t] * rkj); if (lane == t) bon = bt; }
;         float p = 1.f, cs_ = 0.f, ip[16];
; #pragma unroll
;         for (int t = 0; t < 16; ++t) { const float pm1 = p; cs_ += ww[t]; p = __expf(cs_); ip[t] = __expf(-cs_);
;             LAt[t * 64 + lane] = (unsigned short)f2bf(aa[t] * pm1); LRt[t * 64 + lane] = (unsigned short)f2bf(rr[t] * p);
;             LBt[t * 64 + lane] = (unsigned short)f2bf(bb[t] * ip[t]); LKt[t * 64 + lane] = (unsigned short)f2bf(k2[t] * ip[t]); }
	v_fma_f32 v176, -v175, v174, v173
	v_fmac_f32_e32 v174, v176, v178
	v_fma_f32 v173, -v175, v174, v173
	v_div_fmas_f32 v173, v173, v178, v174
	v_div_fixup_f32 v62, v173, v172, v62
	v_pk_mul_f32 v[172:173], v[66:67], v[66:67]
	v_mov_b32_e32 v174, 0
	v_lshlrev_b32_e32 v175, 16, v171
	v_add_f32_dpp v172, v172, v172 quad_perm:[1,0,3,2] row_mask:0xf bank_mask:0xf bound_ctrl:1
	v_add_f32_dpp v173, v173, v173 quad_perm:[1,0,3,2] row_mask:0xf bank_mask:0xf bound_ctrl:1
	v_xor_b32_e32 v182, 0x80000000, v62
	v_add_f32_dpp v172, v172, v172 quad_perm:[2,3,0,1] row_mask:0xf bank_mask:0xf bound_ctrl:1
	v_add_f32_dpp v173, v173, v173 quad_perm:[2,3,0,1] row_mask:0xf bank_mask:0xf bound_ctrl:1
	s_nop 0
	v_add_f32_dpp v172, v172, v172 row_half_mirror row_mask:0xf bank_mask:0xf bound_ctrl:1
	v_add_f32_dpp v173, v173, v173 row_half_mirror row_mask:0xf bank_mask:0xf bound_ctrl:1
	s_nop 0
	v_add_f32_dpp v172, v172, v172 row_mirror row_mask:0xf bank_mask:0xf bound_ctrl:1
	v_add_f32_dpp v173, v173, v173 row_mirror row_mask:0xf bank_mask:0xf bound_ctrl:1
	s_nop 0
	v_mov_b32_dpp v174, v172 row_bcast:15 row_mask:0xa bank_mask:0xf
	v_add_f32_e32 v172, v172, v174
	v_mov_b32_e32 v174, 0
	v_mov_b32_dpp v177, v173 row_bcast:15 row_mask:0xa bank_mask:0xf
	v_add_f32_e32 v173, v173, v177
	v_mov_b32_dpp v174, v172 row_bcast:31 row_mask:0xc bank_mask:0xf
	v_add_f32_e32 v172, v172, v174
	v_mov_b32_e32 v177, 0
	v_readlane_b32 s6, v172, 63
	s_nop 0
	v_mov_b32_dpp v177, v173 row_bcast:31 row_mask:0xc bank_mask:0xf
	v_mul_f32_e32 v172, s6, v140
	v_mov_b32_e32 v174, s6
	v_cmp_lt_f32_e32 vcc, s6, v139
	v_add_f32_e32 v173, v173, v177
	s_nop 0
	v_cndmask_b32_e32 v172, v174, v172, vcc
	v_sqrt_f32_e32 v176, v172
	v_lshlrev_b32_e32 v174, 16, v166
	v_readlane_b32 s6, v173, 63
	v_add_u32_e32 v166, -1, v176
	v_fma_f32 v171, -v166, v176, v172
	v_cmp_ge_f32_e64 s[52:53], 0, v171
	v_mul_f32_e32 v173, s6, v140
	v_mov_b32_e32 v177, s6
	v_cndmask_b32_e64 v166, v176, v166, s[52:53]
	v_cmp_lt_f32_e64 s[52:53], s6, v139
	v_add_u32_e32 v171, 1, v176
	v_fma_f32 v176, -v171, v176, v172
	v_cndmask_b32_e64 v173, v177, v173, s[52:53]
	v_sqrt_f32_e32 v177, v173
	v_cmp_lt_f32_e64 s[54:55], 0, v176
	s_nop 1
	v_cndmask_b32_e64 v166, v166, v171, s[54:55]
	v_mul_f32_e32 v171, 0x37800000, v166
	v_cndmask_b32_e32 v166, v166, v171, vcc
	v_add_u32_e32 v171, -1, v177
	v_fma_f32 v176, -v171, v177, v173
	v_cmp_ge_f32_e32 vcc, 0, v176
	v_add_u32_e32 v176, 1, v177
	s_nop 0
	v_cndmask_b32_e32 v171, v177, v171, vcc
	v_fma_f32 v177, -v176, v177, v173
	v_cmp_lt_f32_e32 vcc, 0, v177
	s_nop 1
	v_cndmask_b32_e32 v171, v171, v176, vcc
	v_mul_f32_e32 v176, 0x37800000, v171
	v_cndmask_b32_e64 v171, v171, v176, s[52:53]
	v_cmp_class_f32_e32 vcc, v173, v134
	s_nop 1
	v_cndmask_b32_e32 v171, v171, v173, vcc
	v_max_f32_e32 v171, 0x2b8cbccc, v171
	v_div_scale_f32 v173, s[6:7], v171, v171, v67
	v_rcp_f32_e32 v176, v173
	v_cmp_class_f32_e32 vcc, v172, v134
	s_nop 1
	v_cndmask_b32_e32 v166, v166, v172, vcc
	v_fma_f32 v172, -v173, v176, 1.0
	v_fmac_f32_e32 v176, v172, v176
	v_div_scale_f32 v172, vcc, v67, v171, v67
	v_mul_f32_e32 v177, v172, v176
	v_fma_f32 v178, -v173, v177, v172
	v_max_f32_e32 v166, 0x2b8cbccc, v166
	v_fmac_f32_e32 v177, v178, v176
	v_fma_f32 v172, -v173, v177, v172
	v_div_scale_f32 v173, s[6:7], v166, v166, v66
	v_rcp_f32_e32 v178, v173
	v_div_fmas_f32 v172, v172, v176, v177
	v_div_fixup_f32 v67, v172, v171, v67
	v_fma_f32 v171, -v173, v178, 1.0
	v_fmac_f32_e32 v178, v171, v178
	v_div_scale_f32 v171, vcc, v66, v166, v66
	v_mul_f32_e32 v172, v171, v178
	v_fma_f32 v176, -v173, v172, v171
	v_fmac_f32_e32 v172, v176, v178
	v_pk_mul_f32 v[176:177], v[62:63], v[174:175]
	v_pk_add_f32 v[174:175], v[174:175], -1.0 op_sel_hi:[1,0]
	v_fma_f32 v171, -v173, v172, v171
	v_pk_fma_f32 v[174:175], v[2:3], v[174:175], 1.0 op_sel_hi:[0,1,0]
	v_pk_mul_f32 v[60:61], v[60:61], v[174:175]
	v_lshlrev_b32_e32 v173, 16, v162
	v_mul_f32_e32 v162, v163, v60
	v_mul_f32_e32 v163, v3, v162
	v_div_fmas_f32 v171, v171, v178, v172
	v_lshlrev_b32_e32 v172, 16, v164
	v_mov_b32_dpp v163, v163 quad_perm:[1,0,3,2] row_mask:0xf bank_mask:0xf bound_ctrl:1
	v_fmac_f32_e32 v163, v3, v162
	v_bfe_u32 v62, v182, 16, 1
	v_add3_u32 v62, v182, v62, s66
	v_add_f32_dpp v162, v163, v163 quad_perm:[2,3,0,1] row_mask:0xf bank_mask:0xf bound_ctrl:1
	v_mov_b32_e32 v163, 0
	v_pk_mul_f32 v[176:177], v[68:69], v[176:177]
	v_add_f32_dpp v162, v162, v162 row_half_mirror row_mask:0xf bank_mask:0xf bound_ctrl:1
	ds_write_b16_d16_hi v114, v62
	v_bfe_u32 v62, v176, 16, 1
	v_add_f32_dpp v162, v162, v162 row_mirror row_mask:0xf bank_mask:0xf bound_ctrl:1
	v_div_fixup_f32 v66, v171, v166, v66
	v_add3_u32 v62, v176, v62, s66
	v_mov_b32_dpp v163, v162 row_bcast:15 row_mask:0xa bank_mask:0xf
	v_add_f32_e32 v162, v162, v163
	v_mov_b32_e32 v163, 0
	ds_write_b16_d16_hi v114, v62 offset:4096
	v_mul_f32_e64 v62, v180, -v66
	v_mov_b32_dpp v163, v162 row_bcast:31 row_mask:0xc bank_mask:0xf
	v_add_f32_e32 v162, v162, v163
	v_pk_mul_f32 v[178:179], v[66:67], v[172:173]
	v_readlane_b32 s6, v162, 63
	v_pk_add_f32 v[162:163], v[172:173], -1.0 op_sel_hi:[1,0]
	v_bfe_u32 v66, v62, 16, 1
	v_pk_fma_f32 v[162:163], v[2:3], v[162:163], 1.0 op_sel_hi:[0,1,0]
	v_pk_mul_f32 v[64:65], v[64:65], v[162:163]
	v_add3_u32 v62, v62, v66, s66
	v_mul_f32_e32 v160, v160, v64
	v_mul_f32_e32 v162, v3, v160
	v_pk_mul_f32 v[178:179], v[70:71], v[178:179]
	ds_write_b16_d16_hi v114, v62 offset:128
	v_mov_b32_dpp v162, v162 quad_perm:[1,0,3,2] row_mask:0xf bank_mask:0xf bound_ctrl:1
	v_fmac_f32_e32 v162, v3, v160
	v_bfe_u32 v62, v178, 16, 1
	v_add3_u32 v62, v178, v62, s66
	v_add_f32_dpp v160, v162, v162 quad_perm:[2,3,0,1] row_mask:0xf bank_mask:0xf bound_ctrl:1
; __device__ __forceinline__ unsigned f2bf(float f) { unsigned u = __builtin_bit_cast(unsigned, f); return (u + 0x7fffu + ((u >> 16) & 1u)) >> 16; }
; __device__ __forceinline__ unsigned pk2(float lo, float hi) { return f2bf(lo) | (f2bf(hi) << 16); }
; __device__ __forceinline__ void scan_pre(const Ctx& C, const bf16* P, const float* mu, const float* k_k, const float* k_a, const float* r_k,
;                                          const bf16* SW, const bf16* SA, const bf16* SV, const bf16* GG, unsigned char* CH) {
;     ...
;             float kk = k * kkj; const float nrm = sqrtf(wave_sum_dpp(kk * kk)); kk = kk / fmaxf(nrm, 1e-12f);
;             rr[t] = r; aa[t] = -kk; bb[t] = kk * as; k2[t] = k * (1.f + (as - 1.f) * kaj);
;             const float bt = wave_sum_dpp(r * k2[t] * rkj); if (lane == t) bon = bt; }
;         float p = 1.f, cs_ = 0.f, ip[16];
; #pragma unroll
;         for (int t = 0; t < 16; ++t) { const float pm1 = p; cs_ += ww[t]; p = __expf(cs_); ip[t] = __expf(-cs_);
;             LAt[t * 64 + lane] = (unsigned short)f2bf(aa[t] * pm1); LRt[t * 64 + lane] = (unsigned short)f2bf(rr[t] * p);
;             LBt[t * 64 + lane] = (unsigned short)f2bf(bb[t] * ip[t]); LKt[t * 64 + lane] = (unsigned short)f2bf(k2[t] * ip[t]); }
; #pragma unroll
;         for (int gg = 0; gg < 4; ++gg) { v4u o;
;             o.x = pk2(bb[4 * gg] * ip[4 * gg] * p, bb[4 * gg + 1] * ip[4 * gg + 1] * p); o.y = pk2(bb[4 * gg + 2] * ip[4 * gg + 2] * p, bb[4 * gg + 3] * ip[4 * gg + 3] * p);
;             o.z = pk2(k2[4 * gg] * ip[4 * gg] * p, k2[4 * gg + 1] * ip[4 * gg + 1] * p); o.w = pk2(k2[4 * gg + 2] * ip[4 * gg + 2] * p, k2[4 * gg + 3] * ip[4 * gg + 3] * p);
;             *(v4u*)(rec + CH_BK + (lane * 4 + gg) * 16) = o; }
	v_mov_b32_e32 v162, 0
	ds_write_b16_d16_hi v114, v62 offset:4224
	v_add_f32_dpp v160, v160, v160 row_half_mirror row_mask:0xf bank_mask:0xf bound_ctrl:1
	v_mul_f32_e64 v62, v181, -v63
	v_bfe_u32 v63, v62, 16, 1
	v_add_f32_dpp v160, v160, v160 row_mirror row_mask:0xf bank_mask:0xf bound_ctrl:1
	v_add3_u32 v62, v62, v63, s66
	ds_write_b16_d16_hi v114, v62 offset:256
	v_mov_b32_dpp v162, v160 row_bcast:15 row_mask:0xa bank_mask:0xf
	v_add_f32_e32 v160, v160, v162
	v_mov_b32_e32 v162, 0
	v_bfe_u32 v62, v177, 16, 1
	v_add3_u32 v62, v177, v62, s66
	v_mov_b32_dpp v162, v160 row_bcast:31 row_mask:0xc bank_mask:0xf
	v_add_f32_e32 v160, v160, v162
	ds_write_b16_d16_hi v114, v62 offset:4352
	v_readlane_b32 s7, v160, 63
	v_mul_f32_e32 v160, v161, v61
	v_mul_f32_e32 v161, v3, v160
	v_pk_mul_f32 v[60:61], v[68:69], v[60:61]
	v_mul_f32_e64 v62, v185, -v67
	v_mov_b32_dpp v161, v161 quad_perm:[1,0,3,2] row_mask:0xf bank_mask:0xf bound_ctrl:1
	v_fmac_f32_e32 v161, v3, v160
	v_bfe_u32 v68, v60, 16, 1
	v_add3_u32 v68, v60, v68, s66
	v_add_f32_dpp v160, v161, v161 quad_perm:[2,3,0,1] row_mask:0xf bank_mask:0xf bound_ctrl:1
	v_mov_b32_e32 v161, 0
	ds_write_b16_d16_hi v114, v68 offset:6144
	v_add_f32_dpp v160, v160, v160 row_half_mirror row_mask:0xf bank_mask:0xf bound_ctrl:1
	v_bfe_u32 v63, v62, 16, 1
	v_add3_u32 v62, v62, v63, s66
	v_add_f32_dpp v160, v160, v160 row_mirror row_mask:0xf bank_mask:0xf bound_ctrl:1
	ds_write_b16_d16_hi v114, v62 offset:384
	v_bfe_u32 v62, v179, 16, 1
	v_mov_b32_dpp v161, v160 row_bcast:15 row_mask:0xa bank_mask:0xf
	v_add_f32_e32 v160, v160, v161
	v_mov_b32_e32 v161, 0
	v_add3_u32 v62, v179, v62, s66
	v_pk_mul_f32 v[66:67], v[178:179], v[8:9] op_sel_hi:[1,0]
	v_mov_b32_dpp v161, v160 row_bcast:31 row_mask:0xc bank_mask:0xf
	v_add_f32_e32 v160, v160, v161
	ds_write_b16_d16_hi v114, v62 offset:4480
	v_readlane_b32 s8, v160, 63
	v_mul_f32_e32 v160, v165, v65
	v_pk_mul_f32 v[64:65], v[70:71], v[64:65]
	v_pk_mul_f32 v[62:63], v[176:177], v[8:9] op_sel_hi:[1,0]
	v_bfe_u32 v68, v64, 16, 1
	v_add3_u32 v68, v64, v68, s66
	ds_write_b16_d16_hi v114, v68 offset:6272
	v_bfe_u32 v68, v61, 16, 1
	v_add3_u32 v68, v61, v68, s66
	ds_write_b16_d16_hi v114, v68 offset:6400
	v_bfe_u32 v68, v65, 16, 1
	v_add3_u32 v68, v65, v68, s66
	ds_write_b16_d16_hi v114, v68 offset:6528
	v_pk_mul_f32 v[64:65], v[64:65], v[8:9] op_sel_hi:[1,0]
	v_bfe_u32 v68, v67, 16, 1
	v_bfe_u32 v69, v66, 16, 1
	v_pk_mul_f32 v[60:61], v[60:61], v[8:9] op_sel_hi:[1,0]
	v_bfe_u32 v70, v65, 16, 1
	v_bfe_u32 v71, v64, 16, 1
	v_add3_u32 v66, v66, v69, s66
	v_add3_u32 v67, v67, v68, s66
	v_bfe_u32 v68, v62, 16, 1
	v_bfe_u32 v69, v63, 16, 1
	v_add3_u32 v64, v64, v71, s66
	v_add3_u32 v65, v65, v70, s66
	v_bfe_u32 v70, v60, 16, 1
	v_bfe_u32 v71, v61, 16, 1
	v_add3_u32 v63, v63, v69, s66
	v_add3_u32 v62, v62, v68, s66
	v_add3_u32 v61, v61, v71, s66
	v_add3_u32 v60, v60, v70, s66
	v_lshrrev_b32_e32 v62, 16, v62
	v_lshrrev_b32_e32 v63, 16, v63
	v_lshrrev_b32_e32 v68, 16, v60
	v_lshrrev_b32_e32 v69, 16, v61
	v_and_or_b32 v61, v67, s67, v63
	v_and_or_b32 v60, v66, s67, v62
	v_pk_mul_f32 v[66:67], v[6:7], v[44:45] op_sel_hi:[0,1]
	v_and_or_b32 v63, v65, s67, v69
	v_and_or_b32 v62, v64, s67, v68
	v_pk_mul_f32 v[68:69], v[66:67], v[66:67]
	v_lshl_add_u64 v[64:65], s[84:85], 0, v[46:47]
	v_mov_b32_e32 v6, 0
	v_add_f32_dpp v26, v68, v68 quad_perm:[1,0,3,2] row_mask:0xf bank_mask:0xf bound_ctrl:1
	v_mul_f32_e32 v161, v3, v160
	s_nop 0
	v_add_f32_dpp v26, v26, v26 quad_perm:[2,3,0,1] row_mask:0xf bank_mask:0xf bound_ctrl:1
	v_mov_b32_dpp v161, v161 quad_perm:[1,0,3,2] row_mask:0xf bank_mask:0xf bound_ctrl:1
	v_fmac_f32_e32 v161, v3, v160
	v_add_f32_dpp v26, v26, v26 row_half_mirror row_mask:0xf bank_mask:0xf bound_ctrl:1
	s_nop 0
	v_add_f32_dpp v160, v161, v161 quad_perm:[2,3,0,1] row_mask:0xf bank_mask:0xf bound_ctrl:1
	v_add_f32_dpp v26, v26, v26 row_mirror row_mask:0xf bank_mask:0xf bound_ctrl:1
	v_mov_b32_e32 v161, 0
	v_add_f32_dpp v160, v160, v160 row_half_mirror row_mask:0xf bank_mask:0xf bound_ctrl:1
	v_mov_b32_dpp v27, v26 row_bcast:15 row_mask:0xa bank_mask:0xf
	v_add_f32_e32 v26, v26, v27
	v_mov_b32_e32 v27, 0
	v_add_f32_dpp v160, v160, v160 row_mirror row_mask:0xf bank_mask:0xf bound_ctrl:1
	s_nop 0
	v_mov_b32_dpp v27, v26 row_bcast:31 row_mask:0xc bank_mask:0xf
	v_add_f32_e32 v26, v26, v27
	v_mov_b32_dpp v161, v160 row_bcast:15 row_mask:0xa bank_mask:0xf
	v_readlane_b32 s10, v26, 63
	v_add_f32_e32 v160, v160, v161
	v_mov_b32_e32 v161, 0
	v_mul_f32_e32 v26, s10, v140
	v_mov_b32_e32 v27, s10
	v_cmp_lt_f32_e32 vcc, s10, v139
	s_mov_b32 s10, 0x69001000
	v_mov_b32_dpp v161, v160 row_bcast:31 row_mask:0xc bank_mask:0xf
	v_cndmask_b32_e32 v68, v27, v26, vcc
	v_add_co_u32_e64 v26, s[52:53], s10, v64
	v_sqrt_f32_e32 v70, v68
	s_nop 0
	v_addc_co_u32_e64 v27, s[52:53], 0, v65, s[52:53]
	global_store_dwordx4 v[26:27], v[60:63], off
	v_mov_b32_e32 v64, 0
	v_add_f32_e32 v160, v160, v161
	v_add_f32_dpp v63, v69, v69 quad_perm:[1,0,3,2] row_mask:0xf bank_mask:0xf bound_ctrl:1
	v_add_u32_e32 v60, -1, v70
	v_fma_f32 v61, -v60, v70, v68
	v_add_f32_dpp v63, v63, v63 quad_perm:[2,3,0,1] row_mask:0xf bank_mask:0xf bound_ctrl:1
	v_cmp_ge_f32_e64 s[52:53], 0, v61
	v_add_u32_e32 v61, 1, v70
	v_add_f32_dpp v63, v63, v63 row_half_mirror row_mask:0xf bank_mask:0xf bound_ctrl:1
	v_cndmask_b32_e64 v60, v70, v60, s[52:53]
	v_fma_f32 v62, -v61, v70, v68
	v_add_f32_dpp v63, v63, v63 row_mirror row_mask:0xf bank_mask:0xf bound_ctrl:1
	v_cmp_lt_f32_e64 s[54:55], 0, v62
	v_mov_b32_e32 v69, 0
	v_mov_b32_dpp v64, v63 row_bcast:15 row_mask:0xa bank_mask:0xf
	v_add_f32_e32 v63, v63, v64
	v_mov_b32_e32 v64, 0
; __device__ __forceinline__ unsigned f2bf(float f) { unsigned u = __builtin_bit_cast(unsigned, f); return (u + 0x7fffu + ((u >> 16) & 1u)) >> 16; }
; __device__ __forceinline__ void scan_pre(const Ctx& C, const bf16* P, const float* mu, const float* k_k, const float* k_a, const float* r_k,
;                                          const bf16* SW, const bf16* SA, const bf16* SV, const bf16* GG, unsigned char* CH) {
;     ...
;             float kk = k * kkj; const float nrm = sqrtf(wave_sum_dpp(kk * kk)); kk = kk / fmaxf(nrm, 1e-12f);
;             rr[t] = r; aa[t] = -kk; bb[t] = kk * as; k2[t] = k * (1.f + (as - 1.f) * kaj);
;             const float bt = wave_sum_dpp(r * k2[t] * rkj); if (lane == t) bon = bt; }
;         float p = 1.f, cs_ = 0.f, ip[16];
; #pragma unroll
;         for (int t = 0; t < 16; ++t) { const float pm1 = p; cs_ += ww[t]; p = __expf(cs_); ip[t] = __expf(-cs_);
;             LAt[t * 64 + lane] = (unsigned short)f2bf(aa[t] * pm1); LRt[t * 64 + lane] = (unsigned short)f2bf(rr[t] * p);
;             LBt[t * 64 + lane] = (unsigned short)f2bf(bb[t] * ip[t]); LKt[t * 64 + lane] = (unsigned short)f2bf(k2[t] * ip[t]); }
	v_cndmask_b32_e64 v60, v60, v61, s[54:55]
	v_mul_f32_e32 v61, 0x37800000, v60
	v_mov_b32_dpp v64, v63 row_bcast:31 row_mask:0xc bank_mask:0xf
	v_add_f32_e32 v63, v63, v64
	v_cndmask_b32_e32 v60, v60, v61, vcc
	v_readlane_b32 s10, v63, 63
	v_readlane_b32 s9, v160, 63
	s_nop 0
	v_mul_f32_e32 v63, s10, v140
	v_mov_b32_e32 v64, s10
	v_cmp_lt_f32_e64 s[52:53], s10, v139
	s_nop 1
	v_cndmask_b32_e64 v63, v64, v63, s[52:53]
	v_sqrt_f32_e32 v64, v63
	s_nop 0
	v_add_u32_e32 v61, -1, v64
	v_fma_f32 v62, -v61, v64, v63
	v_cmp_ge_f32_e32 vcc, 0, v62
	v_add_u32_e32 v62, 1, v64
	s_nop 0
	v_cndmask_b32_e32 v61, v64, v61, vcc
	v_fma_f32 v64, -v62, v64, v63
	v_cmp_lt_f32_e32 vcc, 0, v64
	s_nop 1
	v_cndmask_b32_e32 v61, v61, v62, vcc
	v_mul_f32_e32 v62, 0x37800000, v61
	v_cndmask_b32_e64 v61, v61, v62, s[52:53]
	v_cmp_class_f32_e32 vcc, v63, v134
	s_nop 1
	v_cndmask_b32_e32 v61, v61, v63, vcc
	v_max_f32_e32 v61, 0x2b8cbccc, v61
	v_div_scale_f32 v62, s[10:11], v61, v61, v67
	v_rcp_f32_e32 v63, v62
	v_cmp_class_f32_e32 vcc, v68, v134
	v_fma_f32 v64, -v62, v63, 1.0
	s_nop 0
	v_cndmask_b32_e32 v60, v60, v68, vcc
	v_fmac_f32_e32 v63, v64, v63
	v_div_scale_f32 v64, vcc, v67, v61, v67
	v_mul_f32_e32 v65, v64, v63
	v_fma_f32 v68, -v62, v65, v64
	v_max_f32_e32 v60, 0x2b8cbccc, v60
	v_fmac_f32_e32 v65, v68, v63
	v_fma_f32 v62, -v62, v65, v64
	v_div_scale_f32 v64, s[10:11], v60, v60, v66
	v_rcp_f32_e32 v68, v64
	v_div_fmas_f32 v62, v62, v63, v65
	v_div_fixup_f32 v61, v62, v61, v67
	v_fma_f32 v62, -v64, v68, 1.0
	v_fmac_f32_e32 v68, v62, v68
	v_div_scale_f32 v62, vcc, v66, v60, v66
	v_mul_f32_e32 v63, v62, v68
	v_fma_f32 v65, -v64, v63, v62
	v_fmac_f32_e32 v63, v65, v68
	v_fma_f32 v62, -v64, v63, v62
	v_div_fmas_f32 v64, v62, v68, v63
	v_pk_mul_f32 v[62:63], v[38:39], v[38:39]
	v_mov_b32_e32 v65, 0
	v_div_fixup_f32 v60, v64, v60, v66
	v_add_f32_dpp v62, v62, v62 quad_perm:[1,0,3,2] row_mask:0xf bank_mask:0xf bound_ctrl:1
	v_add_f32_dpp v63, v63, v63 quad_perm:[1,0,3,2] row_mask:0xf bank_mask:0xf bound_ctrl:1
	v_lshlrev_b32_e32 v64, 16, v158
	v_add_f32_dpp v62, v62, v62 quad_perm:[2,3,0,1] row_mask:0xf bank_mask:0xf bound_ctrl:1
	v_add_f32_dpp v63, v63, v63 quad_perm:[2,3,0,1] row_mask:0xf bank_mask:0xf bound_ctrl:1
	s_nop 0
	v_add_f32_dpp v62, v62, v62 row_half_mirror row_mask:0xf bank_mask:0xf bound_ctrl:1
	v_add_f32_dpp v63, v63, v63 row_half_mirror row_mask:0xf bank_mask:0xf bound_ctrl:1
	s_nop 0
	v_add_f32_dpp v62, v62, v62 row_mirror row_mask:0xf bank_mask:0xf bound_ctrl:1
	v_add_f32_dpp v63, v63, v63 row_mirror row_mask:0xf bank_mask:0xf bound_ctrl:1
	s_nop 0
	v_mov_b32_dpp v65, v62 row_bcast:15 row_mask:0xa bank_mask:0xf
	v_add_f32_e32 v62, v62, v65
	v_mov_b32_e32 v65, 0
	v_mov_b32_dpp v69, v63 row_bcast:15 row_mask:0xa bank_mask:0xf
	v_add_f32_e32 v63, v63, v69
	v_mov_b32_dpp v65, v62 row_bcast:31 row_mask:0xc bank_mask:0xf
	v_add_f32_e32 v62, v62, v65
	v_mov_b32_e32 v69, 0
	v_readlane_b32 s10, v62, 63
	s_nop 0
	v_mov_b32_dpp v69, v63 row_bcast:31 row_mask:0xc bank_mask:0xf
	v_mul_f32_e32 v62, s10, v140
	v_mov_b32_e32 v65, s10
	v_cmp_lt_f32_e32 vcc, s10, v139
	v_add_f32_e32 v63, v63, v69
	s_nop 0
	v_cndmask_b32_e32 v62, v65, v62, vcc
	v_sqrt_f32_e32 v67, v62
	v_readlane_b32 s10, v63, 63
	v_lshlrev_b32_e32 v65, 16, v159
	v_add_u32_e32 v66, -1, v67
	v_fma_f32 v68, -v66, v67, v62
	v_cmp_ge_f32_e64 s[52:53], 0, v68
	v_mul_f32_e32 v63, s10, v140
	v_mov_b32_e32 v69, s10
	v_cndmask_b32_e64 v66, v67, v66, s[52:53]
	v_cmp_lt_f32_e64 s[52:53], s10, v139
	v_add_u32_e32 v68, 1, v67
	v_fma_f32 v67, -v68, v67, v62
	v_cndmask_b32_e64 v63, v69, v63, s[52:53]
	v_sqrt_f32_e32 v69, v63
	v_cmp_lt_f32_e64 s[54:55], 0, v67
	s_nop 1
	v_cndmask_b32_e64 v66, v66, v68, s[54:55]
	v_mul_f32_e32 v67, 0x37800000, v66
	v_cndmask_b32_e32 v66, v66, v67, vcc
	v_add_u32_e32 v67, -1, v69
	v_fma_f32 v68, -v67, v69, v63
	v_cmp_ge_f32_e32 vcc, 0, v68
	v_add_u32_e32 v68, 1, v69
	s_nop 0
	v_cndmask_b32_e32 v67, v69, v67, vcc
	v_fma_f32 v69, -v68, v69, v63
	v_cmp_lt_f32_e32 vcc, 0, v69
	s_nop 1
	v_cndmask_b32_e32 v67, v67, v68, vcc
	v_mul_f32_e32 v68, 0x37800000, v67
	v_cndmask_b32_e64 v67, v67, v68, s[52:53]
	v_cmp_class_f32_e32 vcc, v63, v134
	s_nop 1
	v_cndmask_b32_e32 v63, v67, v63, vcc
	v_max_f32_e32 v63, 0x2b8cbccc, v63
	v_div_scale_f32 v67, s[10:11], v63, v63, v39
	v_rcp_f32_e32 v68, v67
	v_cmp_class_f32_e32 vcc, v62, v134
	s_nop 1
	v_cndmask_b32_e32 v62, v66, v62, vcc
	v_fma_f32 v66, -v67, v68, 1.0
	v_fmac_f32_e32 v68, v66, v68
	v_div_scale_f32 v66, vcc, v39, v63, v39
	v_mul_f32_e32 v69, v66, v68
	v_fma_f32 v70, -v67, v69, v66
	v_max_f32_e32 v62, 0x2b8cbccc, v62
	v_fmac_f32_e32 v69, v70, v68
	v_fma_f32 v66, -v67, v69, v66
	v_div_scale_f32 v67, s[10:11], v62, v62, v38
	v_rcp_f32_e32 v70, v67
	v_div_fmas_f32 v66, v66, v68, v69
	v_div_fixup_f32 v39, v66, v63, v39
	v_fma_f32 v63, -v67, v70, 1.0
	v_fmac_f32_e32 v70, v63, v70
	v_div_scale_f32 v63, vcc, v38, v62, v38
	v_mul_f32_e32 v66, v63, v70
	v_fma_f32 v68, -v67, v66, v63
	v_fmac_f32_e32 v66, v68, v70
	v_fma_f32 v63, -v67, v66, v63
	v_div_fmas_f32 v63, v63, v70, v66
	v_div_fixup_f32 v38, v63, v62, v38
	v_lshlrev_b32_e32 v63, 16, v157
	v_lshlrev_b32_e32 v62, 16, v156
	v_pk_mul_f32 v[68:69], v[38:39], v[62:63]
	v_pk_add_f32 v[62:63], v[62:63], -1.0 op_sel_hi:[1,0]
	v_pk_mul_f32 v[66:67], v[60:61], v[64:65]
	v_pk_fma_f32 v[62:63], v[2:3], v[62:63], 1.0 op_sel_hi:[0,1,0]
	v_pk_mul_f32 v[36:37], v[36:37], v[62:63]
	v_pk_add_f32 v[64:65], v[64:65], -1.0 op_sel_hi:[1,0]
	v_mul_f32_e32 v62, v150, v36
	v_mul_f32_e32 v63, v3, v62
	v_pk_fma_f32 v[64:65], v[2:3], v[64:65], 1.0 op_sel_hi:[0,1,0]
	v_mul_f32_e64 v60, v167, -v60
; __device__ __forceinline__ unsigned f2bf(float f) { unsigned u = __builtin_bit_cast(unsigned, f); return (u + 0x7fffu + ((u >> 16) & 1u)) >> 16; }
; __device__ __forceinline__ unsigned pk2(float lo, float hi) { return f2bf(lo) | (f2bf(hi) << 16); }
; __device__ __forceinline__ void scan_pre(const Ctx& C, const bf16* P, const float* mu, const float* k_k, const float* k_a, const float* r_k,
;                                          const bf16* SW, const bf16* SA, const bf16* SV, const bf16* GG, unsigned char* CH) {
;     ...
;             float kk = k * kkj; const float nrm = sqrtf(wave_sum_dpp(kk * kk)); kk = kk / fmaxf(nrm, 1e-12f);
;             rr[t] = r; aa[t] = -kk; bb[t] = kk * as; k2[t] = k * (1.f + (as - 1.f) * kaj);
;             const float bt = wave_sum_dpp(r * k2[t] * rkj); if (lane == t) bon = bt; }
;         float p = 1.f, cs_ = 0.f, ip[16];
; #pragma unroll
;         for (int t = 0; t < 16; ++t) { const float pm1 = p; cs_ += ww[t]; p = __expf(cs_); ip[t] = __expf(-cs_);
;             LAt[t * 64 + lane] = (unsigned short)f2bf(aa[t] * pm1); LRt[t * 64 + lane] = (unsigned short)f2bf(rr[t] * p);
;             LBt[t * 64 + lane] = (unsigned short)f2bf(bb[t] * ip[t]); LKt[t * 64 + lane] = (unsigned short)f2bf(k2[t] * ip[t]); }
; #pragma unroll
;         for (int gg = 0; gg < 4; ++gg) { v4u o;
;             o.x = pk2(bb[4 * gg] * ip[4 * gg] * p, bb[4 * gg + 1] * ip[4 * gg + 1] * p); o.y = pk2(bb[4 * gg + 2] * ip[4 * gg + 2] * p, bb[4 * gg + 3] * ip[4 * gg + 3] * p);
;             o.z = pk2(k2[4 * gg] * ip[4 * gg] * p, k2[4 * gg + 1] * ip[4 * gg + 1] * p); o.w = pk2(k2[4 * gg + 2] * ip[4 * gg + 2] * p, k2[4 * gg + 3] * ip[4 * gg + 3] * p);
;             *(v4u*)(rec + CH_BK + (lane * 4 + gg) * 16) = o; }
	v_mov_b32_dpp v63, v63 quad_perm:[1,0,3,2] row_mask:0xf bank_mask:0xf bound_ctrl:1
	v_fmac_f32_e32 v63, v3, v62
	v_pk_mul_f32 v[44:45], v[44:45], v[64:65]
	v_bfe_u32 v70, v60, 16, 1
	v_add_f32_dpp v62, v63, v63 quad_perm:[2,3,0,1] row_mask:0xf bank_mask:0xf bound_ctrl:1
	v_mov_b32_e32 v63, 0
	v_add3_u32 v60, v60, v70, s66
	v_add_f32_dpp v62, v62, v62 row_half_mirror row_mask:0xf bank_mask:0xf bound_ctrl:1
	v_pk_mul_f32 v[66:67], v[40:41], v[66:67]
	ds_write_b16_d16_hi v114, v60 offset:512
	v_add_f32_dpp v62, v62, v62 row_mirror row_mask:0xf bank_mask:0xf bound_ctrl:1
	v_bfe_u32 v60, v66, 16, 1
	v_add3_u32 v60, v66, v60, s66
	v_mov_b32_dpp v63, v62 row_bcast:15 row_mask:0xa bank_mask:0xf
	v_add_f32_e32 v62, v62, v63
	v_mov_b32_e32 v63, 0
	v_mul_f32_e64 v38, v168, -v38
	ds_write_b16_d16_hi v114, v60 offset:4608
	v_mov_b32_dpp v63, v62 row_bcast:31 row_mask:0xc bank_mask:0xf
	v_add_f32_e32 v62, v62, v63
	v_bfe_u32 v60, v38, 16, 1
	v_readlane_b32 s11, v62, 63
	v_mul_f32_e32 v62, v148, v45
	v_mul_f32_e32 v63, v3, v62
	v_add3_u32 v38, v38, v60, s66
	v_pk_mul_f32 v[68:69], v[42:43], v[68:69]
	v_mov_b32_dpp v63, v63 quad_perm:[1,0,3,2] row_mask:0xf bank_mask:0xf bound_ctrl:1
	v_fmac_f32_e32 v63, v3, v62
	ds_write_b16_d16_hi v114, v38 offset:640
	v_bfe_u32 v38, v68, 16, 1
	v_add_f32_dpp v62, v63, v63 quad_perm:[2,3,0,1] row_mask:0xf bank_mask:0xf bound_ctrl:1
	v_mov_b32_e32 v63, 0
	v_add3_u32 v38, v68, v38, s66
	v_add_f32_dpp v62, v62, v62 row_half_mirror row_mask:0xf bank_mask:0xf bound_ctrl:1
	ds_write_b16_d16_hi v114, v38 offset:4736
	v_mul_f32_e64 v38, v169, -v61
	v_add_f32_dpp v62, v62, v62 row_mirror row_mask:0xf bank_mask:0xf bound_ctrl:1
	v_bfe_u32 v60, v38, 16, 1
	v_add3_u32 v38, v38, v60, s66
	v_mov_b32_dpp v63, v62 row_bcast:15 row_mask:0xa bank_mask:0xf
	v_add_f32_e32 v62, v62, v63
	v_mov_b32_e32 v63, 0
	ds_write_b16_d16_hi v114, v38 offset:768
	v_bfe_u32 v38, v67, 16, 1
	v_mov_b32_dpp v63, v62 row_bcast:31 row_mask:0xc bank_mask:0xf
	v_add_f32_e32 v62, v62, v63
	v_add3_u32 v38, v67, v38, s66
	v_readlane_b32 s12, v62, 63
	v_mul_f32_e32 v62, v149, v37
	v_pk_mul_f32 v[36:37], v[42:43], v[36:37]
	ds_write_b16_d16_hi v114, v38 offset:4864
	v_bfe_u32 v42, v36, 16, 1
	v_mul_f32_e64 v38, v170, -v39
	v_pk_mul_f32 v[40:41], v[40:41], v[44:45]
	v_add3_u32 v42, v36, v42, s66
	v_bfe_u32 v39, v38, 16, 1
	ds_write_b16_d16_hi v114, v42 offset:6784
	v_bfe_u32 v42, v41, 16, 1
	v_add3_u32 v38, v38, v39, s66
	v_add3_u32 v42, v41, v42, s66
	ds_write_b16_d16_hi v114, v38 offset:896
	v_bfe_u32 v38, v69, 16, 1
	v_mul_f32_e32 v64, v151, v44
	v_bfe_u32 v44, v40, 16, 1
	ds_write_b16_d16_hi v114, v42 offset:6912
	v_bfe_u32 v42, v37, 16, 1
	v_add3_u32 v38, v69, v38, s66
	v_pk_mul_f32 v[60:61], v[68:69], v[8:9] op_sel_hi:[1,0]
	v_add3_u32 v44, v40, v44, s66
	v_add3_u32 v42, v37, v42, s66
	v_pk_mul_f32 v[36:37], v[36:37], v[8:9] op_sel_hi:[1,0]
	ds_write_b16_d16_hi v114, v38 offset:4992
	v_pk_mul_f32 v[38:39], v[66:67], v[8:9] op_sel_hi:[1,0]
	ds_write_b16_d16_hi v114, v44 offset:6656
	ds_write_b16_d16_hi v114, v42 offset:7040
	v_pk_mul_f32 v[40:41], v[40:41], v[8:9] op_sel_hi:[1,0]
	v_bfe_u32 v42, v61, 16, 1
	v_bfe_u32 v43, v60, 16, 1
	v_bfe_u32 v44, v37, 16, 1
	v_bfe_u32 v45, v36, 16, 1
	v_add3_u32 v43, v60, v43, s66
	v_add3_u32 v42, v61, v42, s66
	v_add3_u32 v45, v36, v45, s66
	v_add3_u32 v44, v37, v44, s66
	v_bfe_u32 v36, v38, 16, 1
	v_bfe_u32 v37, v39, 16, 1
	v_bfe_u32 v60, v40, 16, 1
	v_bfe_u32 v61, v41, 16, 1
	v_add3_u32 v37, v39, v37, s66
	v_add3_u32 v36, v38, v36, s66
	v_add3_u32 v38, v41, v61, s66
	v_add3_u32 v39, v40, v60, s66
	v_pk_mul_f32 v[40:41], v[34:35], v[34:35]
	v_lshrrev_b32_e32 v60, 16, v39
	v_lshrrev_b32_e32 v36, 16, v36
	v_add_f32_dpp v39, v40, v40 quad_perm:[1,0,3,2] row_mask:0xf bank_mask:0xf bound_ctrl:1
	v_mov_b32_e32 v40, 0
	v_lshrrev_b32_e32 v37, 16, v37
	v_add_f32_dpp v39, v39, v39 quad_perm:[2,3,0,1] row_mask:0xf bank_mask:0xf bound_ctrl:1
	v_lshrrev_b32_e32 v38, 16, v38
	v_and_or_b32 v37, v42, s67, v37
	v_add_f32_dpp v39, v39, v39 row_half_mirror row_mask:0xf bank_mask:0xf bound_ctrl:1
	v_and_or_b32 v36, v43, s67, v36
	v_mov_b32_e32 v43, 0
	v_add_f32_dpp v39, v39, v39 row_mirror row_mask:0xf bank_mask:0xf bound_ctrl:1
	v_mul_f32_e32 v65, v3, v64
	v_mul_f32_e32 v63, v3, v62
	v_mov_b32_dpp v40, v39 row_bcast:15 row_mask:0xa bank_mask:0xf
	v_add_f32_e32 v39, v39, v40
	v_mov_b32_e32 v40, 0
	v_mov_b32_dpp v65, v65 quad_perm:[1,0,3,2] row_mask:0xf bank_mask:0xf bound_ctrl:1
	v_mov_b32_dpp v63, v63 quad_perm:[1,0,3,2] row_mask:0xf bank_mask:0xf bound_ctrl:1
	v_mov_b32_dpp v40, v39 row_bcast:31 row_mask:0xc bank_mask:0xf
	v_add_f32_e32 v39, v39, v40
	v_fmac_f32_e32 v65, v3, v64
	v_readlane_b32 s14, v39, 63
	v_fmac_f32_e32 v63, v3, v62
	v_add_f32_dpp v64, v65, v65 quad_perm:[2,3,0,1] row_mask:0xf bank_mask:0xf bound_ctrl:1
	v_mul_f32_e32 v39, s14, v140
	v_mov_b32_e32 v40, s14
	v_cmp_lt_f32_e32 vcc, s14, v139
	v_add_f32_dpp v62, v63, v63 quad_perm:[2,3,0,1] row_mask:0xf bank_mask:0xf bound_ctrl:1
	v_add_f32_dpp v64, v64, v64 row_half_mirror row_mask:0xf bank_mask:0xf bound_ctrl:1
	v_cndmask_b32_e32 v40, v40, v39, vcc
	v_and_or_b32 v39, v44, s67, v38
	v_and_or_b32 v38, v45, s67, v60
	global_store_dwordx4 v[26:27], v[36:39], off offset:16
	v_sqrt_f32_e32 v42, v40
	v_add_f32_dpp v62, v62, v62 row_half_mirror row_mask:0xf bank_mask:0xf bound_ctrl:1
	v_add_f32_dpp v39, v41, v41 quad_perm:[1,0,3,2] row_mask:0xf bank_mask:0xf bound_ctrl:1
	v_mov_b32_e32 v41, 0
	v_add_u32_e32 v36, -1, v42
	v_add_f32_dpp v39, v39, v39 quad_perm:[2,3,0,1] row_mask:0xf bank_mask:0xf bound_ctrl:1
	v_fma_f32 v37, -v36, v42, v40
	v_cmp_ge_f32_e64 s[52:53], 0, v37
; __device__ __forceinline__ void scan_pre(const Ctx& C, const bf16* P, const float* mu, const float* k_k, const float* k_a, const float* r_k,
;                                          const bf16* SW, const bf16* SA, const bf16* SV, const bf16* GG, unsigned char* CH) {
;     ...
;             float kk = k * kkj; const float nrm = sqrtf(wave_sum_dpp(kk * kk)); kk = kk / fmaxf(nrm, 1e-12f);
;             rr[t] = r; aa[t] = -kk; bb[t] = kk * as; k2[t] = k * (1.f + (as - 1.f) * kaj);
	v_add_f32_dpp v39, v39, v39 row_half_mirror row_mask:0xf bank_mask:0xf bound_ctrl:1
	v_add_u32_e32 v37, 1, v42
	v_cndmask_b32_e64 v36, v42, v36, s[52:53]
	v_add_f32_dpp v39, v39, v39 row_mirror row_mask:0xf bank_mask:0xf bound_ctrl:1
	v_fma_f32 v38, -v37, v42, v40
	v_cmp_lt_f32_e64 s[54:55], 0, v38
	v_mov_b32_dpp v41, v39 row_bcast:15 row_mask:0xa bank_mask:0xf
	v_add_f32_e32 v39, v39, v41
	v_mov_b32_e32 v41, 0
	v_cndmask_b32_e64 v36, v36, v37, s[54:55]
	v_mul_f32_e32 v37, 0x37800000, v36
	v_mov_b32_dpp v41, v39 row_bcast:31 row_mask:0xc bank_mask:0xf
	v_add_f32_e32 v39, v39, v41
	v_cndmask_b32_e32 v36, v36, v37, vcc
	v_readlane_b32 s14, v39, 63
	v_add_f32_dpp v64, v64, v64 row_mirror row_mask:0xf bank_mask:0xf bound_ctrl:1
	v_mov_b32_e32 v65, 0
	v_mul_f32_e32 v39, s14, v140
	v_mov_b32_e32 v41, s14
	v_cmp_lt_f32_e64 s[52:53], s14, v139
	v_add_f32_dpp v62, v62, v62 row_mirror row_mask:0xf bank_mask:0xf bound_ctrl:1
	v_mov_b32_e32 v63, 0
	v_cndmask_b32_e64 v39, v41, v39, s[52:53]
	v_sqrt_f32_e32 v41, v39
	v_mov_b32_dpp v65, v64 row_bcast:15 row_mask:0xa bank_mask:0xf
	v_mov_b32_dpp v63, v62 row_bcast:15 row_mask:0xa bank_mask:0xf
	v_lshl_add_u64 v[60:61], s[84:85], 0, v[50:51]
	v_add_u32_e32 v37, -1, v41
	v_fma_f32 v38, -v37, v41, v39
	v_cmp_ge_f32_e32 vcc, 0, v38
	v_add_u32_e32 v38, 1, v41
	v_add_f32_e32 v64, v64, v65
	v_cndmask_b32_e32 v37, v41, v37, vcc
	v_fma_f32 v41, -v38, v41, v39
	v_cmp_lt_f32_e32 vcc, 0, v41
	v_mov_b32_e32 v65, 0
	v_add_f32_e32 v62, v62, v63
	v_cndmask_b32_e32 v37, v37, v38, vcc
	v_mul_f32_e32 v38, 0x37800000, v37
	v_cndmask_b32_e64 v37, v37, v38, s[52:53]
	v_cmp_class_f32_e32 vcc, v39, v134
	v_mov_b32_e32 v63, 0
	v_mov_b32_dpp v65, v64 row_bcast:31 row_mask:0xc bank_mask:0xf
	v_cndmask_b32_e32 v37, v37, v39, vcc
	v_max_f32_e32 v37, 0x2b8cbccc, v37
	v_div_scale_f32 v38, s[14:15], v37, v37, v35
	v_rcp_f32_e32 v39, v38
	v_cmp_class_f32_e32 vcc, v40, v134
	v_mov_b32_dpp v63, v62 row_bcast:31 row_mask:0xc bank_mask:0xf
	v_add_f32_e32 v64, v64, v65
	v_cndmask_b32_e32 v36, v36, v40, vcc
	v_max_f32_e32 v40, 0x2b8cbccc, v36
	v_fma_f32 v36, -v38, v39, 1.0
	v_fmac_f32_e32 v39, v36, v39
	v_div_scale_f32 v36, vcc, v35, v37, v35
	v_mul_f32_e32 v41, v36, v39
	v_fma_f32 v42, -v38, v41, v36
	v_fmac_f32_e32 v41, v42, v39
	v_fma_f32 v36, -v38, v41, v36
	v_div_scale_f32 v38, s[14:15], v40, v40, v34
	v_rcp_f32_e32 v42, v38
	v_div_fmas_f32 v36, v36, v39, v41
	v_div_fixup_f32 v35, v36, v37, v35
	v_add_f32_e32 v62, v62, v63
	v_fma_f32 v36, -v38, v42, 1.0
	v_fmac_f32_e32 v42, v36, v42
	v_div_scale_f32 v36, vcc, v34, v40, v34
	v_mul_f32_e32 v37, v36, v42
	v_fma_f32 v39, -v38, v37, v36
	v_fmac_f32_e32 v37, v39, v42
	v_fma_f32 v36, -v38, v37, v36
	v_div_fmas_f32 v38, v36, v42, v37
	v_pk_mul_f32 v[36:37], v[30:31], v[30:31]
	v_mov_b32_e32 v39, 0
	v_div_fixup_f32 v34, v38, v40, v34
	v_add_f32_dpp v36, v36, v36 quad_perm:[1,0,3,2] row_mask:0xf bank_mask:0xf bound_ctrl:1
	v_add_f32_dpp v37, v37, v37 quad_perm:[1,0,3,2] row_mask:0xf bank_mask:0xf bound_ctrl:1
	v_lshlrev_b32_e32 v38, 16, v145
	v_add_f32_dpp v36, v36, v36 quad_perm:[2,3,0,1] row_mask:0xf bank_mask:0xf bound_ctrl:1
	v_add_f32_dpp v37, v37, v37 quad_perm:[2,3,0,1] row_mask:0xf bank_mask:0xf bound_ctrl:1
	v_readlane_b32 s10, v64, 63
	v_add_f32_dpp v36, v36, v36 row_half_mirror row_mask:0xf bank_mask:0xf bound_ctrl:1
	v_add_f32_dpp v37, v37, v37 row_half_mirror row_mask:0xf bank_mask:0xf bound_ctrl:1
	v_readlane_b32 s13, v62, 63
	v_add_f32_dpp v36, v36, v36 row_mirror row_mask:0xf bank_mask:0xf bound_ctrl:1
	v_add_f32_dpp v37, v37, v37 row_mirror row_mask:0xf bank_mask:0xf bound_ctrl:1
	s_nop 0
	v_mov_b32_dpp v39, v36 row_bcast:15 row_mask:0xa bank_mask:0xf
	v_add_f32_e32 v36, v36, v39
	v_mov_b32_e32 v39, 0
	v_mov_b32_dpp v43, v37 row_bcast:15 row_mask:0xa bank_mask:0xf
	v_add_f32_e32 v37, v37, v43
	v_mov_b32_dpp v39, v36 row_bcast:31 row_mask:0xc bank_mask:0xf
	v_add_f32_e32 v36, v36, v39
	v_mov_b32_e32 v43, 0
	v_readlane_b32 s14, v36, 63
	s_nop 0
	v_mov_b32_dpp v43, v37 row_bcast:31 row_mask:0xc bank_mask:0xf
	v_mul_f32_e32 v36, s14, v140
	v_mov_b32_e32 v39, s14
	v_cmp_lt_f32_e32 vcc, s14, v139
	v_add_f32_e32 v37, v37, v43
	s_nop 0
	v_cndmask_b32_e32 v36, v39, v36, vcc
	v_sqrt_f32_e32 v41, v36
	v_readlane_b32 s14, v37, 63
	s_waitcnt vmcnt(16)
	v_lshlrev_b32_e32 v39, 16, v147
	v_add_u32_e32 v40, -1, v41
	v_fma_f32 v42, -v40, v41, v36
	v_cmp_ge_f32_e64 s[52:53], 0, v42
	v_mul_f32_e32 v37, s14, v140
	v_mov_b32_e32 v43, s14
	v_cndmask_b32_e64 v40, v41, v40, s[52:53]
	v_cmp_lt_f32_e64 s[52:53], s14, v139
	v_add_u32_e32 v42, 1, v41
	v_fma_f32 v41, -v42, v41, v36
	v_cndmask_b32_e64 v37, v43, v37, s[52:53]
	v_sqrt_f32_e32 v43, v37
	v_cmp_lt_f32_e64 s[54:55], 0, v41
	s_nop 1
	v_cndmask_b32_e64 v40, v40, v42, s[54:55]
	v_mul_f32_e32 v41, 0x37800000, v40
	v_cndmask_b32_e32 v40, v40, v41, vcc
	v_add_u32_e32 v41, -1, v43
	v_fma_f32 v42, -v41, v43, v37
	v_cmp_ge_f32_e32 vcc, 0, v42
	v_add_u32_e32 v42, 1, v43
	s_nop 0
	v_cndmask_b32_e32 v41, v43, v41, vcc
	v_fma_f32 v43, -v42, v43, v37
	v_cmp_lt_f32_e32 vcc, 0, v43
	s_nop 1
	v_cndmask_b32_e32 v41, v41, v42, vcc
	v_mul_f32_e32 v42, 0x37800000, v41
	v_cndmask_b32_e64 v41, v41, v42, s[52:53]
	v_cmp_class_f32_e32 vcc, v37, v134
	s_nop 1
	v_cndmask_b32_e32 v37, v41, v37, vcc
	v_max_f32_e32 v37, 0x2b8cbccc, v37
	v_div_scale_f32 v41, s[14:15], v37, v37, v31
	v_rcp_f32_e32 v42, v41
	v_cmp_class_f32_e32 vcc, v36, v134
	s_nop 1
	v_cndmask_b32_e32 v36, v40, v36, vcc
	v_fma_f32 v40, -v41, v42, 1.0
	v_fmac_f32_e32 v42, v40, v42
	v_div_scale_f32 v40, vcc, v31, v37, v31
	v_mul_f32_e32 v43, v40, v42
	v_fma_f32 v44, -v41, v43, v40
	v_max_f32_e32 v36, 0x2b8cbccc, v36
	v_fmac_f32_e32 v43, v44, v42
	v_fma_f32 v40, -v41, v43, v40
	v_div_scale_f32 v41, s[14:15], v36, v36, v30
	v_rcp_f32_e32 v44, v41
	v_div_fmas_f32 v40, v40, v42, v43
	v_div_fixup_f32 v31, v40, v37, v31
	v_fma_f32 v37, -v41, v44, 1.0
	v_fmac_f32_e32 v44, v37, v44
	v_div_scale_f32 v37, vcc, v30, v36, v30
	v_mul_f32_e32 v40, v37, v44
	v_fma_f32 v42, -v41, v40, v37
	v_fmac_f32_e32 v40, v42, v44
	v_fma_f32 v37, -v41, v40, v37
	v_div_fmas_f32 v37, v37, v44, v40
	v_div_fixup_f32 v30, v37, v36, v30
	s_waitcnt vmcnt(12)
; __device__ __forceinline__ unsigned f2bf(float f) { unsigned u = __builtin_bit_cast(unsigned, f); return (u + 0x7fffu + ((u >> 16) & 1u)) >> 16; }
; __device__ __forceinline__ unsigned pk2(float lo, float hi) { return f2bf(lo) | (f2bf(hi) << 16); }
; __device__ __forceinline__ void scan_pre(const Ctx& C, const bf16* P, const float* mu, const float* k_k, const float* k_a, const float* r_k,
;                                          const bf16* SW, const bf16* SA, const bf16* SV, const bf16* GG, unsigned char* CH) {
;     ...
;             float kk = k * kkj; const float nrm = sqrtf(wave_sum_dpp(kk * kk)); kk = kk / fmaxf(nrm, 1e-12f);
;             rr[t] = r; aa[t] = -kk; bb[t] = kk * as; k2[t] = k * (1.f + (as - 1.f) * kaj);
;             const float bt = wave_sum_dpp(r * k2[t] * rkj); if (lane == t) bon = bt; }
;         float p = 1.f, cs_ = 0.f, ip[16];
; #pragma unroll
;         for (int t = 0; t < 16; ++t) { const float pm1 = p; cs_ += ww[t]; p = __expf(cs_); ip[t] = __expf(-cs_);
;             LAt[t * 64 + lane] = (unsigned short)f2bf(aa[t] * pm1); LRt[t * 64 + lane] = (unsigned short)f2bf(rr[t] * p);
;             LBt[t * 64 + lane] = (unsigned short)f2bf(bb[t] * ip[t]); LKt[t * 64 + lane] = (unsigned short)f2bf(k2[t] * ip[t]); }
; #pragma unroll
;         for (int gg = 0; gg < 4; ++gg) { v4u o;
;             o.x = pk2(bb[4 * gg] * ip[4 * gg] * p, bb[4 * gg + 1] * ip[4 * gg + 1] * p); o.y = pk2(bb[4 * gg + 2] * ip[4 * gg + 2] * p, bb[4 * gg + 3] * ip[4 * gg + 3] * p);
;             o.z = pk2(k2[4 * gg] * ip[4 * gg] * p, k2[4 * gg + 1] * ip[4 * gg + 1] * p); o.w = pk2(k2[4 * gg + 2] * ip[4 * gg + 2] * p, k2[4 * gg + 3] * ip[4 * gg + 3] * p);
;             *(v4u*)(rec + CH_BK + (lane * 4 + gg) * 16) = o; }
	v_lshlrev_b32_e32 v37, 16, v146
	v_lshlrev_b32_e32 v36, 16, v142
	v_pk_mul_f32 v[42:43], v[30:31], v[36:37]
	v_pk_add_f32 v[36:37], v[36:37], -1.0 op_sel_hi:[1,0]
	v_pk_mul_f32 v[40:41], v[34:35], v[38:39]
	v_pk_fma_f32 v[36:37], v[2:3], v[36:37], 1.0 op_sel_hi:[0,1,0]
	v_pk_mul_f32 v[28:29], v[28:29], v[36:37]
	v_mul_f32_e64 v34, v152, -v34
	v_mul_f32_e32 v36, v108, v28
	v_mul_f32_e32 v37, v3, v36
	v_bfe_u32 v44, v34, 16, 1
	v_add3_u32 v34, v34, v44, s66
	v_mov_b32_dpp v37, v37 quad_perm:[1,0,3,2] row_mask:0xf bank_mask:0xf bound_ctrl:1
	v_fmac_f32_e32 v37, v3, v36
	v_pk_mul_f32 v[40:41], v[22:23], v[40:41]
	ds_write_b16_d16_hi v114, v34 offset:1024
	v_add_f32_dpp v36, v37, v37 quad_perm:[2,3,0,1] row_mask:0xf bank_mask:0xf bound_ctrl:1
	v_bfe_u32 v34, v40, 16, 1
	v_add3_u32 v34, v40, v34, s66
	v_add_f32_dpp v36, v36, v36 row_half_mirror row_mask:0xf bank_mask:0xf bound_ctrl:1
	v_mul_f32_e64 v30, v153, -v30
	v_mov_b32_e32 v37, 0
	v_add_f32_dpp v36, v36, v36 row_mirror row_mask:0xf bank_mask:0xf bound_ctrl:1
	ds_write_b16_d16_hi v114, v34 offset:5120
	v_bfe_u32 v34, v30, 16, 1
	v_mov_b32_dpp v37, v36 row_bcast:15 row_mask:0xa bank_mask:0xf
	v_add3_u32 v30, v30, v34, s66
	v_pk_mul_f32 v[42:43], v[24:25], v[42:43]
	v_pk_add_f32 v[38:39], v[38:39], -1.0 op_sel_hi:[1,0]
	v_add_f32_e32 v36, v36, v37
	v_mov_b32_e32 v37, 0
	ds_write_b16_d16_hi v114, v30 offset:1152
	v_bfe_u32 v30, v42, 16, 1
	v_pk_fma_f32 v[38:39], v[2:3], v[38:39], 1.0 op_sel_hi:[0,1,0]
	v_mov_b32_dpp v37, v36 row_bcast:31 row_mask:0xc bank_mask:0xf
	v_add3_u32 v30, v42, v30, s66
	v_pk_mul_f32 v[32:33], v[32:33], v[38:39]
	v_add_f32_e32 v36, v36, v37
	ds_write_b16_d16_hi v114, v30 offset:5248
	v_mul_f32_e64 v30, v154, -v35
	v_readlane_b32 s15, v36, 63
	v_mul_f32_e32 v36, v143, v33
	v_bfe_u32 v34, v30, 16, 1
	v_mul_f32_e32 v37, v3, v36
	v_add3_u32 v30, v30, v34, s66
	ds_write_b16_d16_hi v114, v30 offset:1280
	v_mov_b32_dpp v37, v37 quad_perm:[1,0,3,2] row_mask:0xf bank_mask:0xf bound_ctrl:1
	v_bfe_u32 v30, v41, 16, 1
	v_fmac_f32_e32 v37, v3, v36
	v_pk_mul_f32 v[24:25], v[24:25], v[28:29]
	v_add3_u32 v30, v41, v30, s66
	v_add_f32_dpp v36, v37, v37 quad_perm:[2,3,0,1] row_mask:0xf bank_mask:0xf bound_ctrl:1
	v_bfe_u32 v28, v24, 16, 1
	ds_write_b16_d16_hi v114, v30 offset:5376
	v_mul_f32_e64 v30, v155, -v31
	v_add_f32_dpp v36, v36, v36 row_half_mirror row_mask:0xf bank_mask:0xf bound_ctrl:1
	v_pk_mul_f32 v[22:23], v[22:23], v[32:33]
	v_add3_u32 v28, v24, v28, s66
	v_bfe_u32 v31, v30, 16, 1
	v_add_f32_dpp v36, v36, v36 row_mirror row_mask:0xf bank_mask:0xf bound_ctrl:1
	v_mov_b32_e32 v37, 0
	ds_write_b16_d16_hi v114, v28 offset:7296
	v_bfe_u32 v28, v23, 16, 1
	v_add3_u32 v30, v30, v31, s66
	v_mov_b32_dpp v37, v36 row_bcast:15 row_mask:0xa bank_mask:0xf
	v_add3_u32 v28, v23, v28, s66
	ds_write_b16_d16_hi v114, v30 offset:1408
	v_bfe_u32 v30, v43, 16, 1
	v_mul_f32_e32 v38, v109, v32
	v_add_f32_e32 v36, v36, v37
	v_mov_b32_e32 v37, 0
	v_bfe_u32 v32, v22, 16, 1
	ds_write_b16_d16_hi v114, v28 offset:7424
	v_bfe_u32 v28, v25, 16, 1
	v_add3_u32 v30, v43, v30, s66
	v_mov_b32_dpp v37, v36 row_bcast:31 row_mask:0xc bank_mask:0xf
	v_add3_u32 v32, v22, v32, s66
	v_add3_u32 v28, v25, v28, s66
	v_pk_mul_f32 v[24:25], v[24:25], v[8:9] op_sel_hi:[1,0]
	ds_write_b16_d16_hi v114, v30 offset:5504
	v_pk_mul_f32 v[30:31], v[40:41], v[8:9] op_sel_hi:[1,0]
	v_pk_mul_f32 v[34:35], v[42:43], v[8:9] op_sel_hi:[1,0]
	v_add_f32_e32 v36, v36, v37
	ds_write_b16_d16_hi v114, v32 offset:7168
	v_bfe_u32 v32, v25, 16, 1
	v_bfe_u32 v33, v24, 16, 1
	v_readlane_b32 s16, v36, 63
	v_mul_f32_e32 v36, v144, v29
	ds_write_b16_d16_hi v114, v28 offset:7552
	v_pk_mul_f32 v[22:23], v[22:23], v[8:9] op_sel_hi:[1,0]
	v_bfe_u32 v28, v35, 16, 1
	v_bfe_u32 v29, v34, 16, 1
	v_add3_u32 v24, v24, v33, s66
	v_add3_u32 v25, v25, v32, s66
	v_bfe_u32 v32, v30, 16, 1
	v_bfe_u32 v33, v31, 16, 1
	v_add3_u32 v29, v34, v29, s66
	v_add3_u32 v28, v35, v28, s66
	v_bfe_u32 v34, v22, 16, 1
	v_bfe_u32 v35, v23, 16, 1
	v_add3_u32 v31, v31, v33, s66
	v_add3_u32 v30, v30, v32, s66
	v_add3_u32 v23, v23, v35, s66
	v_add3_u32 v22, v22, v34, s66
	v_lshrrev_b32_e32 v30, 16, v30
	v_lshrrev_b32_e32 v31, 16, v31
	v_lshrrev_b32_e32 v32, 16, v22
	v_lshrrev_b32_e32 v33, 16, v23
	v_and_or_b32 v23, v28, s67, v31
	v_and_or_b32 v22, v29, s67, v30
	v_pk_mul_f32 v[28:29], v[20:21], v[20:21]
	v_mov_b32_e32 v30, 0
	v_and_or_b32 v25, v25, s67, v33
	v_add_f32_dpp v28, v28, v28 quad_perm:[1,0,3,2] row_mask:0xf bank_mask:0xf bound_ctrl:1
	v_and_or_b32 v24, v24, s67, v32
	global_store_dwordx4 v[26:27], v[22:25], off offset:32
	v_add_f32_dpp v28, v28, v28 quad_perm:[2,3,0,1] row_mask:0xf bank_mask:0xf bound_ctrl:1
	v_mul_f32_e32 v39, v3, v38
	v_add_f32_dpp v25, v29, v29 quad_perm:[1,0,3,2] row_mask:0xf bank_mask:0xf bound_ctrl:1
	v_add_f32_dpp v28, v28, v28 row_half_mirror row_mask:0xf bank_mask:0xf bound_ctrl:1
	v_mov_b32_e32 v29, 0
	v_add_f32_dpp v25, v25, v25 quad_perm:[2,3,0,1] row_mask:0xf bank_mask:0xf bound_ctrl:1
	v_add_f32_dpp v28, v28, v28 row_mirror row_mask:0xf bank_mask:0xf bound_ctrl:1
	v_mul_f32_e32 v37, v3, v36
	v_add_f32_dpp v25, v25, v25 row_half_mirror row_mask:0xf bank_mask:0xf bound_ctrl:1
	v_mov_b32_dpp v30, v28 row_bcast:15 row_mask:0xa bank_mask:0xf
	v_add_f32_e32 v28, v28, v30
	v_mov_b32_e32 v30, 0
	v_add_f32_dpp v25, v25, v25 row_mirror row_mask:0xf bank_mask:0xf bound_ctrl:1
	v_mov_b32_dpp v39, v39 quad_perm:[1,0,3,2] row_mask:0xf bank_mask:0xf bound_ctrl:1
	v_mov_b32_dpp v30, v28 row_bcast:31 row_mask:0xc bank_mask:0xf
	v_add_f32_e32 v28, v28, v30
	v_mov_b32_dpp v29, v25 row_bcast:15 row_mask:0xa bank_mask:0xf
	v_readlane_b32 s18, v28, 63
; __device__ __forceinline__ void scan_pre(const Ctx& C, const bf16* P, const float* mu, const float* k_k, const float* k_a, const float* r_k,
;                                          const bf16* SW, const bf16* SA, const bf16* SV, const bf16* GG, unsigned char* CH) {
;     ...
;             float kk = k * kkj; const float nrm = sqrtf(wave_sum_dpp(kk * kk)); kk = kk / fmaxf(nrm, 1e-12f);
;             rr[t] = r; aa[t] = -kk; bb[t] = kk * as; k2[t] = k * (1.f + (as - 1.f) * kaj);
	v_add_f32_e32 v25, v25, v29
	v_mov_b32_e32 v29, 0
	v_mul_f32_e32 v28, s18, v140
	v_mov_b32_e32 v30, s18
	v_cmp_lt_f32_e32 vcc, s18, v139
	v_mov_b32_dpp v29, v25 row_bcast:31 row_mask:0xc bank_mask:0xf
	v_add_f32_e32 v25, v25, v29
	v_cndmask_b32_e32 v28, v30, v28, vcc
	v_sqrt_f32_e32 v30, v28
	v_readlane_b32 s18, v25, 63
	v_mov_b32_dpp v37, v37 quad_perm:[1,0,3,2] row_mask:0xf bank_mask:0xf bound_ctrl:1
	v_fmac_f32_e32 v39, v3, v38
	v_add_u32_e32 v22, -1, v30
	v_fma_f32 v23, -v22, v30, v28
	v_cmp_ge_f32_e64 s[52:53], 0, v23
	v_mul_f32_e32 v25, s18, v140
	v_mov_b32_e32 v29, s18
	v_cndmask_b32_e64 v22, v30, v22, s[52:53]
	v_cmp_lt_f32_e64 s[52:53], s18, v139
	v_add_u32_e32 v23, 1, v30
	v_fma_f32 v24, -v23, v30, v28
	v_cndmask_b32_e64 v25, v29, v25, s[52:53]
	v_sqrt_f32_e32 v29, v25
	v_cmp_lt_f32_e64 s[54:55], 0, v24
	v_fmac_f32_e32 v37, v3, v36
	v_add_f32_dpp v38, v39, v39 quad_perm:[2,3,0,1] row_mask:0xf bank_mask:0xf bound_ctrl:1
	v_cndmask_b32_e64 v22, v22, v23, s[54:55]
	v_mul_f32_e32 v23, 0x37800000, v22
	v_cndmask_b32_e32 v22, v22, v23, vcc
	v_add_u32_e32 v23, -1, v29
	v_fma_f32 v24, -v23, v29, v25
	v_cmp_ge_f32_e32 vcc, 0, v24
	v_add_u32_e32 v24, 1, v29
	v_add_f32_dpp v36, v37, v37 quad_perm:[2,3,0,1] row_mask:0xf bank_mask:0xf bound_ctrl:1
	v_cndmask_b32_e32 v23, v29, v23, vcc
	v_fma_f32 v29, -v24, v29, v25
	v_cmp_lt_f32_e32 vcc, 0, v29
	v_add_f32_dpp v38, v38, v38 row_half_mirror row_mask:0xf bank_mask:0xf bound_ctrl:1
	v_add_f32_dpp v36, v36, v36 row_half_mirror row_mask:0xf bank_mask:0xf bound_ctrl:1
	v_cndmask_b32_e32 v23, v23, v24, vcc
	v_mul_f32_e32 v24, 0x37800000, v23
	v_cndmask_b32_e64 v23, v23, v24, s[52:53]
	v_cmp_class_f32_e32 vcc, v25, v134
	v_add_f32_dpp v38, v38, v38 row_mirror row_mask:0xf bank_mask:0xf bound_ctrl:1
	v_mov_b32_e32 v39, 0
	v_cndmask_b32_e32 v23, v23, v25, vcc
	v_max_f32_e32 v23, 0x2b8cbccc, v23
	v_div_scale_f32 v24, s[18:19], v23, v23, v21
	v_rcp_f32_e32 v25, v24
	v_cmp_class_f32_e32 vcc, v28, v134
	v_add_f32_dpp v36, v36, v36 row_mirror row_mask:0xf bank_mask:0xf bound_ctrl:1
	v_mov_b32_e32 v37, 0
	v_cndmask_b32_e32 v22, v22, v28, vcc
	v_max_f32_e32 v28, 0x2b8cbccc, v22
	v_fma_f32 v22, -v24, v25, 1.0
	v_fmac_f32_e32 v25, v22, v25
	v_div_scale_f32 v22, vcc, v21, v23, v21
	v_mul_f32_e32 v29, v22, v25
	v_fma_f32 v30, -v24, v29, v22
	v_fmac_f32_e32 v29, v30, v25
	v_fma_f32 v22, -v24, v29, v22
	v_div_scale_f32 v24, s[18:19], v28, v28, v20
	v_rcp_f32_e32 v30, v24
	v_div_fmas_f32 v22, v22, v25, v29
	v_div_fixup_f32 v21, v22, v23, v21
	v_mov_b32_e32 v29, 0
	v_fma_f32 v22, -v24, v30, 1.0
	v_fmac_f32_e32 v30, v22, v30
	v_div_scale_f32 v22, vcc, v20, v28, v20
	v_mul_f32_e32 v23, v22, v30
	v_fma_f32 v25, -v24, v23, v22
	v_fmac_f32_e32 v23, v25, v30
	v_fma_f32 v22, -v24, v23, v22
	v_div_fmas_f32 v24, v22, v30, v23
	v_pk_mul_f32 v[22:23], v[16:17], v[16:17]
	v_div_fixup_f32 v20, v24, v28, v20
	s_waitcnt vmcnt(8)
	v_lshlrev_b32_e32 v25, 16, v107
	v_add_f32_dpp v4, v22, v22 quad_perm:[1,0,3,2] row_mask:0xf bank_mask:0xf bound_ctrl:1
	v_add_f32_dpp v23, v23, v23 quad_perm:[1,0,3,2] row_mask:0xf bank_mask:0xf bound_ctrl:1
	v_lshlrev_b32_e32 v24, 16, v106
	v_add_f32_dpp v4, v4, v4 quad_perm:[2,3,0,1] row_mask:0xf bank_mask:0xf bound_ctrl:1
	v_add_f32_dpp v23, v23, v23 quad_perm:[2,3,0,1] row_mask:0xf bank_mask:0xf bound_ctrl:1
	v_mov_b32_dpp v39, v38 row_bcast:15 row_mask:0xa bank_mask:0xf
	v_add_f32_dpp v4, v4, v4 row_half_mirror row_mask:0xf bank_mask:0xf bound_ctrl:1
	v_add_f32_dpp v23, v23, v23 row_half_mirror row_mask:0xf bank_mask:0xf bound_ctrl:1
	v_mov_b32_dpp v37, v36 row_bcast:15 row_mask:0xa bank_mask:0xf
	v_add_f32_dpp v4, v4, v4 row_mirror row_mask:0xf bank_mask:0xf bound_ctrl:1
	v_add_f32_dpp v23, v23, v23 row_mirror row_mask:0xf bank_mask:0xf bound_ctrl:1
	v_add_f32_e32 v38, v38, v39
	v_mov_b32_dpp v6, v4 row_bcast:15 row_mask:0xa bank_mask:0xf
	v_add_f32_e32 v4, v4, v6
	v_mov_b32_e32 v6, 0
	v_mov_b32_dpp v29, v23 row_bcast:15 row_mask:0xa bank_mask:0xf
	v_add_f32_e32 v23, v23, v29
	v_mov_b32_dpp v6, v4 row_bcast:31 row_mask:0xc bank_mask:0xf
	v_add_f32_e32 v4, v4, v6
	v_mov_b32_e32 v29, 0
	v_readlane_b32 s18, v4, 63
	v_mov_b32_e32 v39, 0
	v_mov_b32_dpp v29, v23 row_bcast:31 row_mask:0xc bank_mask:0xf
	v_mul_f32_e32 v4, s18, v140
	v_mov_b32_e32 v6, s18
	v_cmp_lt_f32_e32 vcc, s18, v139
	v_add_f32_e32 v23, v23, v29
	v_add_f32_e32 v36, v36, v37
	v_cndmask_b32_e32 v4, v6, v4, vcc
	v_sqrt_f32_e32 v6, v4
	v_readlane_b32 s18, v23, 63
	v_mov_b32_e32 v37, 0
	v_mov_b32_dpp v39, v38 row_bcast:31 row_mask:0xc bank_mask:0xf
	v_add_u32_e32 v22, -1, v6
	v_fma_f32 v28, -v22, v6, v4
	v_cmp_ge_f32_e64 s[52:53], 0, v28
	v_mul_f32_e32 v23, s18, v140
	v_mov_b32_e32 v29, s18
	v_cndmask_b32_e64 v22, v6, v22, s[52:53]
	v_cmp_lt_f32_e64 s[52:53], s18, v139
	v_add_u32_e32 v28, 1, v6
	v_fma_f32 v6, -v28, v6, v4
	v_cndmask_b32_e64 v23, v29, v23, s[52:53]
	v_sqrt_f32_e32 v29, v23
	v_cmp_lt_f32_e64 s[54:55], 0, v6
	v_mov_b32_dpp v37, v36 row_bcast:31 row_mask:0xc bank_mask:0xf
	v_add_f32_e32 v38, v38, v39
	v_cndmask_b32_e64 v6, v22, v28, s[54:55]
	v_mul_f32_e32 v22, 0x37800000, v6
	v_cndmask_b32_e32 v6, v6, v22, vcc
	v_add_u32_e32 v22, -1, v29
	v_fma_f32 v28, -v22, v29, v23
	v_cmp_ge_f32_e32 vcc, 0, v28
	v_add_u32_e32 v28, 1, v29
	v_add_f32_e32 v36, v36, v37
	v_cndmask_b32_e32 v22, v29, v22, vcc
	v_fma_f32 v29, -v28, v29, v23
	v_cmp_lt_f32_e32 vcc, 0, v29
	v_readlane_b32 s14, v38, 63
	v_readlane_b32 s17, v36, 63
	v_cndmask_b32_e32 v22, v22, v28, vcc
	v_mul_f32_e32 v28, 0x37800000, v22
	v_cndmask_b32_e64 v22, v22, v28, s[52:53]
	v_cmp_class_f32_e32 vcc, v23, v134
	s_mov_b32 s52, 0x69003000
	s_nop 0
	v_cndmask_b32_e32 v22, v22, v23, vcc
	v_max_f32_e32 v22, 0x2b8cbccc, v22
	v_div_scale_f32 v23, s[18:19], v22, v22, v17
	v_rcp_f32_e32 v28, v23
	v_cmp_class_f32_e32 vcc, v4, v134
	s_nop 1
	v_cndmask_b32_e32 v4, v6, v4, vcc
	v_fma_f32 v6, -v23, v28, 1.0
	v_fmac_f32_e32 v28, v6, v28
	v_div_scale_f32 v6, vcc, v17, v22, v17
	v_mul_f32_e32 v29, v6, v28
	v_fma_f32 v30, -v23, v29, v6
	v_max_f32_e32 v4, 0x2b8cbccc, v4
	v_fmac_f32_e32 v29, v30, v28
	v_fma_f32 v6, -v23, v29, v6
	v_div_scale_f32 v23, s[18:19], v4, v4, v16
	v_rcp_f32_e32 v30, v23
	v_div_fmas_f32 v6, v6, v28, v29
	v_div_fixup_f32 v17, v6, v22, v17
	v_fma_f32 v6, -v23, v30, 1.0
	v_fmac_f32_e32 v30, v6, v30
	v_div_scale_f32 v6, vcc, v16, v4, v16
	v_mul_f32_e32 v22, v6, v30
	v_fma_f32 v28, -v23, v22, v6
	v_fmac_f32_e32 v22, v28, v30
	v_fma_f32 v6, -v23, v22, v6
	v_div_fmas_f32 v6, v6, v30, v22
	v_div_fixup_f32 v16, v6, v4, v16
	v_mul_f32_e64 v4, v110, -v20
	v_pk_mul_f32 v[28:29], v[20:21], v[24:25]
	v_bfe_u32 v6, v4, 16, 1
	v_add3_u32 v4, v4, v6, s66
	v_pk_mul_f32 v[28:29], v[10:11], v[28:29]
	ds_write_b16_d16_hi v114, v4 offset:1536
	v_bfe_u32 v4, v28, 16, 1
	v_add3_u32 v4, v28, v4, s66
	s_waitcnt vmcnt(4)
; __device__ __forceinline__ unsigned f2bf(float f) { unsigned u = __builtin_bit_cast(unsigned, f); return (u + 0x7fffu + ((u >> 16) & 1u)) >> 16; }
; __device__ __forceinline__ unsigned pk2(float lo, float hi) { return f2bf(lo) | (f2bf(hi) << 16); }
; __device__ __forceinline__ void scan_pre(const Ctx& C, const bf16* P, const float* mu, const float* k_k, const float* k_a, const float* r_k,
;                                          const bf16* SW, const bf16* SA, const bf16* SV, const bf16* GG, unsigned char* CH) {
;     ...
;             const float bt = wave_sum_dpp(r * k2[t] * rkj); if (lane == t) bon = bt; }
;         float p = 1.f, cs_ = 0.f, ip[16];
; #pragma unroll
;         for (int t = 0; t < 16; ++t) { const float pm1 = p; cs_ += ww[t]; p = __expf(cs_); ip[t] = __expf(-cs_);
;             LAt[t * 64 + lane] = (unsigned short)f2bf(aa[t] * pm1); LRt[t * 64 + lane] = (unsigned short)f2bf(rr[t] * p);
;             LBt[t * 64 + lane] = (unsigned short)f2bf(bb[t] * ip[t]); LKt[t * 64 + lane] = (unsigned short)f2bf(k2[t] * ip[t]); }
; #pragma unroll
;         for (int gg = 0; gg < 4; ++gg) { v4u o;
;             o.x = pk2(bb[4 * gg] * ip[4 * gg] * p, bb[4 * gg + 1] * ip[4 * gg + 1] * p); o.y = pk2(bb[4 * gg + 2] * ip[4 * gg + 2] * p, bb[4 * gg + 3] * ip[4 * gg + 3] * p);
;             o.z = pk2(k2[4 * gg] * ip[4 * gg] * p, k2[4 * gg + 1] * ip[4 * gg + 1] * p); o.w = pk2(k2[4 * gg + 2] * ip[4 * gg + 2] * p, k2[4 * gg + 3] * ip[4 * gg + 3] * p);
;             *(v4u*)(rec + CH_BK + (lane * 4 + gg) * 16) = o; }
;         *(float*)(rec + CH_PC + lane * 4) = p;
;     ...
;         { v4u o0, o1; o0.x = PKB(vv[0], vv[1]); o0.y = PKB(vv[2], vv[3]); o0.z = PKB(vv[4], vv[5]); o0.w = PKB(vv[6], vv[7]); o1.x = PKB(vv[8], vv[9]); o1.y = PKB(vv[10], vv[11]); o1.z = PKB(vv[12], vv[13]); o1.w = PKB(vv[14], vv[15]);
;           *(v4u*)(rec + CH_VT + lane * 32) = o0; *(v4u*)(rec + CH_VT + lane * 32 + 16) = o1; }
;         { v4u o0, o1; o0.x = PKB(gg_[0], gg_[1]); o0.y = PKB(gg_[2], gg_[3]); o0.z = PKB(gg_[4], gg_[5]); o0.w = PKB(gg_[6], gg_[7]); o1.x = PKB(gg_[8], gg_[9]); o1.y = PKB(gg_[10], gg_[11]); o1.z = PKB(gg_[12], gg_[13]); o1.w = PKB(gg_[14], gg_[15]);
;           *(v4u*)(rec + CH_G + lane * 32) = o0; *(v4u*)(rec + CH_G + lane * 32 + 16) = o1; }
	v_lshlrev_b32_e32 v23, 16, v105
	v_lshlrev_b32_e32 v22, 16, v104
	ds_write_b16_d16_hi v114, v4 offset:5632
	v_mul_f32_e64 v4, v111, -v16
	v_pk_mul_f32 v[30:31], v[16:17], v[22:23]
	v_bfe_u32 v6, v4, 16, 1
	v_add3_u32 v4, v4, v6, s66
	v_pk_mul_f32 v[30:31], v[12:13], v[30:31]
	ds_write_b16_d16_hi v114, v4 offset:1664
	v_bfe_u32 v4, v30, 16, 1
	v_add3_u32 v4, v30, v4, s66
	ds_write_b16_d16_hi v114, v4 offset:5760
	v_mul_f32_e64 v4, v112, -v21
	v_bfe_u32 v6, v4, 16, 1
	v_add3_u32 v4, v4, v6, s66
	ds_write_b16_d16_hi v114, v4 offset:1792
	v_bfe_u32 v4, v29, 16, 1
	v_add3_u32 v4, v29, v4, s66
	ds_write_b16_d16_hi v114, v4 offset:5888
	v_mul_f32_e64 v4, v113, -v17
	v_bfe_u32 v6, v4, 16, 1
	v_add3_u32 v4, v4, v6, s66
	v_pk_add_f32 v[24:25], v[24:25], -1.0 op_sel_hi:[1,0]
	ds_write_b16_d16_hi v114, v4 offset:1920
	v_bfe_u32 v4, v31, 16, 1
	v_pk_fma_f32 v[24:25], v[2:3], v[24:25], 1.0 op_sel_hi:[0,1,0]
	v_add3_u32 v4, v31, v4, s66
	v_pk_mul_f32 v[18:19], v[18:19], v[24:25]
	ds_write_b16_d16_hi v114, v4 offset:6016
	v_mul_f32_e32 v4, v103, v18
	v_mul_f32_e32 v6, v3, v4
	v_pk_add_f32 v[22:23], v[22:23], -1.0 op_sel_hi:[1,0]
	v_pk_mul_f32 v[16:17], v[28:29], v[8:9] op_sel_hi:[1,0]
	v_mov_b32_dpp v6, v6 quad_perm:[1,0,3,2] row_mask:0xf bank_mask:0xf bound_ctrl:1
	v_fmac_f32_e32 v6, v3, v4
	v_pk_fma_f32 v[22:23], v[2:3], v[22:23], 1.0 op_sel_hi:[0,1,0]
	v_pk_mul_f32 v[14:15], v[14:15], v[22:23]
	v_add_f32_dpp v4, v6, v6 quad_perm:[2,3,0,1] row_mask:0xf bank_mask:0xf bound_ctrl:1
	v_mov_b32_e32 v6, 0
	v_mul_f32_e32 v2, v102, v14
	v_add_f32_dpp v4, v4, v4 row_half_mirror row_mask:0xf bank_mask:0xf bound_ctrl:1
	v_pk_mul_f32 v[20:21], v[30:31], v[8:9] op_sel_hi:[1,0]
	s_nop 0
	v_add_f32_dpp v4, v4, v4 row_mirror row_mask:0xf bank_mask:0xf bound_ctrl:1
	s_nop 1
	v_mov_b32_dpp v6, v4 row_bcast:15 row_mask:0xa bank_mask:0xf
	v_add_f32_e32 v4, v4, v6
	v_mov_b32_e32 v6, 0
	s_nop 1
	v_mov_b32_dpp v6, v4 row_bcast:31 row_mask:0xc bank_mask:0xf
	v_add_f32_e32 v4, v4, v6
	v_bfe_u32 v6, v20, 16, 1
	v_readlane_b32 s54, v4, 63
	v_mul_f32_e32 v4, v3, v2
	v_add3_u32 v6, v20, v6, s66
	s_nop 0
	v_mov_b32_dpp v4, v4 quad_perm:[1,0,3,2] row_mask:0xf bank_mask:0xf bound_ctrl:1
	v_fmac_f32_e32 v4, v3, v2
	s_nop 1
	v_add_f32_dpp v2, v4, v4 quad_perm:[2,3,0,1] row_mask:0xf bank_mask:0xf bound_ctrl:1
	v_mov_b32_e32 v4, 0
	s_nop 0
	v_add_f32_dpp v2, v2, v2 row_half_mirror row_mask:0xf bank_mask:0xf bound_ctrl:1
	s_nop 1
	v_add_f32_dpp v2, v2, v2 row_mirror row_mask:0xf bank_mask:0xf bound_ctrl:1
	s_nop 1
	v_mov_b32_dpp v4, v2 row_bcast:15 row_mask:0xa bank_mask:0xf
	v_add_f32_e32 v2, v2, v4
	v_mov_b32_e32 v4, 0
	s_nop 1
	v_mov_b32_dpp v4, v2 row_bcast:31 row_mask:0xc bank_mask:0xf
	v_add_f32_e32 v2, v2, v4
	s_nop 0
	v_readlane_b32 s55, v2, 63
	v_mul_f32_e32 v2, v100, v19
	v_mul_f32_e32 v4, v3, v2
	s_nop 1
	v_mov_b32_dpp v4, v4 quad_perm:[1,0,3,2] row_mask:0xf bank_mask:0xf bound_ctrl:1
	v_fmac_f32_e32 v4, v3, v2
	s_nop 1
	v_add_f32_dpp v2, v4, v4 quad_perm:[2,3,0,1] row_mask:0xf bank_mask:0xf bound_ctrl:1
	v_mov_b32_e32 v4, 0
	s_nop 0
	v_add_f32_dpp v2, v2, v2 row_half_mirror row_mask:0xf bank_mask:0xf bound_ctrl:1
	s_nop 1
	v_add_f32_dpp v2, v2, v2 row_mirror row_mask:0xf bank_mask:0xf bound_ctrl:1
	s_nop 1
	v_mov_b32_dpp v4, v2 row_bcast:15 row_mask:0xa bank_mask:0xf
	v_add_f32_e32 v2, v2, v4
	v_mov_b32_e32 v4, 0
	s_nop 1
	v_mov_b32_dpp v4, v2 row_bcast:31 row_mask:0xc bank_mask:0xf
	v_add_f32_e32 v2, v2, v4
	s_nop 0
	v_readlane_b32 s18, v2, 63
	v_mul_f32_e32 v2, v101, v15
	v_mul_f32_e32 v4, v3, v2
	s_nop 1
	v_mov_b32_dpp v4, v4 quad_perm:[1,0,3,2] row_mask:0xf bank_mask:0xf bound_ctrl:1
	v_fmac_f32_e32 v4, v3, v2
	v_mov_b32_e32 v3, 0
	s_nop 0
	v_add_f32_dpp v2, v4, v4 quad_perm:[2,3,0,1] row_mask:0xf bank_mask:0xf bound_ctrl:1
	s_nop 1
	v_add_f32_dpp v2, v2, v2 row_half_mirror row_mask:0xf bank_mask:0xf bound_ctrl:1
	s_nop 1
	v_add_f32_dpp v2, v2, v2 row_mirror row_mask:0xf bank_mask:0xf bound_ctrl:1
	s_nop 1
	v_mov_b32_dpp v3, v2 row_bcast:15 row_mask:0xa bank_mask:0xf
	v_add_f32_e32 v2, v2, v3
	v_mov_b32_e32 v3, 0
	s_nop 1
	v_mov_b32_dpp v3, v2 row_bcast:31 row_mask:0xc bank_mask:0xf
	v_add_f32_e32 v2, v2, v3
	s_nop 0
	v_readlane_b32 s19, v2, 63
	v_pk_mul_f32 v[2:3], v[10:11], v[18:19]
	v_pk_mul_f32 v[10:11], v[12:13], v[14:15]
	v_bfe_u32 v4, v2, 16, 1
	v_add3_u32 v4, v2, v4, s66
	ds_write_b16_d16_hi v114, v4 offset:7680
	v_bfe_u32 v4, v10, 16, 1
	v_add3_u32 v4, v10, v4, s66
	ds_write_b16_d16_hi v114, v4 offset:7808
	v_bfe_u32 v4, v3, 16, 1
	v_add3_u32 v4, v3, v4, s66
	ds_write_b16_d16_hi v114, v4 offset:7936
	v_bfe_u32 v4, v11, 16, 1
	v_add3_u32 v4, v11, v4, s66
	v_pk_mul_f32 v[10:11], v[10:11], v[8:9] op_sel_hi:[1,0]
	v_pk_mul_f32 v[2:3], v[2:3], v[8:9] op_sel_hi:[1,0]
	v_bfe_u32 v12, v11, 16, 1
	v_bfe_u32 v13, v10, 16, 1
	v_add3_u32 v14, v10, v13, s66
	v_add3_u32 v12, v11, v12, s66
	v_bfe_u32 v10, v16, 16, 1
	v_bfe_u32 v11, v17, 16, 1
	v_bfe_u32 v13, v2, 16, 1
	v_bfe_u32 v15, v3, 16, 1
	ds_write_b16_d16_hi v114, v4 offset:8064
	v_bfe_u32 v4, v21, 16, 1
	v_add3_u32 v11, v17, v11, s66
	v_add3_u32 v10, v16, v10, s66
	v_add3_u32 v3, v3, v15, s66
	v_add3_u32 v2, v2, v13, s66
	v_add3_u32 v4, v21, v4, s66
	v_lshrrev_b32_e32 v10, 16, v10
	v_lshrrev_b32_e32 v11, 16, v11
	v_lshrrev_b32_e32 v2, 16, v2
	v_lshrrev_b32_e32 v3, 16, v3
	v_and_or_b32 v11, v4, s67, v11
	v_and_or_b32 v10, v6, s67, v10
	v_and_or_b32 v13, v12, s67, v3
	v_and_or_b32 v12, v14, s67, v2
	v_lshl_add_u64 v[2:3], s[84:85], 0, v[48:49]
	global_store_dwordx4 v[26:27], v[10:13], off offset:48
	v_lshl_or_b32 v14, v87, 16, v86
	v_lshl_or_b32 v15, v94, 16, v92
	v_add_co_u32_e32 v10, vcc, s52, v2
	s_mov_b32 s52, 0x69002000
	s_nop 0
	v_addc_co_u32_e32 v11, vcc, 0, v3, vcc
	v_add_co_u32_e32 v6, vcc, s52, v60
	global_store_dword v[10:11], v8, off
	v_lshl_or_b32 v11, v7, 16, v76
	v_addc_co_u32_e32 v7, vcc, 0, v61, vcc
	v_lshl_or_b32 v10, v75, 16, v72
	v_lshl_or_b32 v12, v83, 16, v81
	v_lshl_or_b32 v13, v78, 16, v84
	v_add_co_u32_e32 v8, vcc, 0x69003000, v60
	v_lshl_or_b32 v16, v98, 16, v96
	v_lshl_or_b32 v17, v90, 16, v99
	global_store_dwordx4 v[6:7], v[10:13], off
	global_store_dwordx4 v[6:7], v[14:17], off offset:16
	v_lshl_or_b32 v4, v74, 16, v52
	v_lshl_or_b32 v6, v80, 16, v79
	v_lshl_or_b32 v7, v77, 16, v82
	s_waitcnt vmcnt(7)
	v_lshl_or_b32 v13, v9, 16, v97
	v_addc_co_u32_e32 v9, vcc, 0, v61, vcc
	v_lshl_or_b32 v10, v89, 16, v85
	v_lshl_or_b32 v11, v91, 16, v88
	v_lshl_or_b32 v12, v95, 16, v93
	global_store_dwordx4 v[8:9], v[4:7], off offset:320
	global_store_dwordx4 v[8:9], v[10:13], off offset:336
	s_and_saveexec_b64 s[52:53], s[2:3]
	s_cbranch_execz .LBB0_1274
; __device__ __forceinline__ unsigned f2bf(float f) { unsigned u = __builtin_bit_cast(unsigned, f); return (u + 0x7fffu + ((u >> 16) & 1u)) >> 16; }
; __device__ __forceinline__ unsigned pk2(float lo, float hi) { return f2bf(lo) | (f2bf(hi) << 16); }
; __device__ __forceinline__ void scan_pre(const Ctx& C, const bf16* P, const float* mu, const float* k_k, const float* k_a, const float* r_k,
;                                          const bf16* SW, const bf16* SA, const bf16* SV, const bf16* GG, unsigned char* CH) {
;     ...
;             const float bt = wave_sum_dpp(r * k2[t] * rkj); if (lane == t) bon = bt; }
;         float p = 1.f, cs_ = 0.f, ip[16];
; #pragma unroll
;         for (int t = 0; t < 16; ++t) { const float pm1 = p; cs_ += ww[t]; p = __expf(cs_); ip[t] = __expf(-cs_);
;             LAt[t * 64 + lane] = (unsigned short)f2bf(aa[t] * pm1); LRt[t * 64 + lane] = (unsigned short)f2bf(rr[t] * p);
;             LBt[t * 64 + lane] = (unsigned short)f2bf(bb[t] * ip[t]); LKt[t * 64 + lane] = (unsigned short)f2bf(k2[t] * ip[t]); }
; #pragma unroll
;         for (int gg = 0; gg < 4; ++gg) { v4u o;
;             o.x = pk2(bb[4 * gg] * ip[4 * gg] * p, bb[4 * gg + 1] * ip[4 * gg + 1] * p); o.y = pk2(bb[4 * gg + 2] * ip[4 * gg + 2] * p, bb[4 * gg + 3] * ip[4 * gg + 3] * p);
;             o.z = pk2(k2[4 * gg] * ip[4 * gg] * p, k2[4 * gg + 1] * ip[4 * gg + 1] * p); o.w = pk2(k2[4 * gg + 2] * ip[4 * gg + 2] * p, k2[4 * gg + 3] * ip[4 * gg + 3] * p);
;             *(v4u*)(rec + CH_BK + (lane * 4 + gg) * 16) = o; }
;         *(float*)(rec + CH_PC + lane * 4) = p;
;     ...
;         { v4u o0, o1; o0.x = PKB(vv[0], vv[1]); o0.y = PKB(vv[2], vv[3]); o0.z = PKB(vv[4], vv[5]); o0.w = PKB(vv[6], vv[7]); o1.x = PKB(vv[8], vv[9]); o1.y = PKB(vv[10], vv[11]); o1.z = PKB(vv[12], vv[13]); o1.w = PKB(vv[14], vv[15]);
;           *(v4u*)(rec + CH_VT + lane * 32) = o0; *(v4u*)(rec + CH_VT + lane * 32 + 16) = o1; }
;         { v4u o0, o1; o0.x = PKB(gg_[0], gg_[1]); o0.y = PKB(gg_[2], gg_[3]); o0.z = PKB(gg_[4], gg_[5]); o0.w = PKB(gg_[6], gg_[7]); o1.x = PKB(gg_[8], gg_[9]); o1.y = PKB(gg_[10], gg_[11]); o1.z = PKB(gg_[12], gg_[13]); o1.w = PKB(gg_[14], gg_[15]);
;           *(v4u*)(rec + CH_G + lane * 32) = o0; *(v4u*)(rec + CH_G + lane * 32 + 16) = o1; }
;         if (lane < 16) *(float*)(rec + CH_BON + lane * 4) = bon;
	v_mov_b32_e32 v4, s6
	v_cndmask_b32_e64 v4, 0, v4, s[36:37]
	v_mov_b32_e32 v5, s7
	v_cndmask_b32_e64 v4, v4, v5, s[34:35]
	v_mov_b32_e32 v5, s8
	v_cndmask_b32_e64 v4, v4, v5, s[30:31]
	v_mov_b32_e32 v5, s9
	v_cndmask_b32_e64 v4, v4, v5, s[28:29]
	v_mov_b32_e32 v5, s10
	v_cndmask_b32_e64 v4, v4, v5, s[26:27]
	v_mov_b32_e32 v5, s11
	v_cndmask_b32_e64 v4, v4, v5, s[24:25]
	v_mov_b32_e32 v5, s12
	v_cndmask_b32_e64 v4, v4, v5, s[22:23]
	v_mov_b32_e32 v5, s13
	v_readlane_b32 s6, v228, 24
	v_cndmask_b32_e64 v4, v4, v5, s[20:21]
	v_mov_b32_e32 v5, s14
	v_readlane_b32 s7, v228, 25
	v_add_co_u32_e32 v2, vcc, 0x69003000, v2
	s_nop 0
	v_cndmask_b32_e64 v4, v4, v5, s[6:7]
	v_readlane_b32 s6, v228, 22
	v_mov_b32_e32 v5, s15
	v_readlane_b32 s7, v228, 23
	v_addc_co_u32_e32 v3, vcc, 0, v3, vcc
	s_nop 0
	v_cndmask_b32_e64 v4, v4, v5, s[6:7]
	v_readlane_b32 s6, v228, 20
	v_mov_b32_e32 v5, s16
	v_readlane_b32 s7, v228, 21
	s_nop 1
	v_cndmask_b32_e64 v4, v4, v5, s[6:7]
	v_readlane_b32 s6, v228, 18
	v_mov_b32_e32 v5, s17
	v_readlane_b32 s7, v228, 19
	s_nop 1
	v_cndmask_b32_e64 v4, v4, v5, s[6:7]
	v_readlane_b32 s6, v228, 16
	v_mov_b32_e32 v5, s54
	v_readlane_b32 s7, v228, 17
	s_nop 1
	v_cndmask_b32_e64 v4, v4, v5, s[6:7]
	v_readlane_b32 s6, v228, 14
	v_mov_b32_e32 v5, s55
	v_readlane_b32 s7, v228, 15
	s_nop 1
	v_cndmask_b32_e64 v4, v4, v5, s[6:7]
	v_readlane_b32 s6, v228, 12
	v_mov_b32_e32 v5, s18
	v_readlane_b32 s7, v228, 13
	s_nop 1
	v_cndmask_b32_e64 v4, v4, v5, s[6:7]
	v_readlane_b32 s6, v228, 10
	v_mov_b32_e32 v5, s19
	v_readlane_b32 s7, v228, 11
	s_nop 1
	v_cndmask_b32_e64 v4, v4, v5, s[6:7]
	global_store_dword v[2:3], v4, off offset:256
